# p1 + per-unit tile-mapping division replaced by shift/mask + first-trip counted waits relaxed past the epilogue stores (vmcnt(24)), GEMM prologue drains its staging loads
# speedup vs baseline: 1.0052x; 1.0004x over previous
.LBB0_162:
	v_lshl_add_u64 v[148:149], v[138:139], 0, s[62:63]
	s_add_i32 m0, s13, 0x18000
	s_waitcnt vmcnt(2)
	s_barrier
	global_load_lds_dwordx4 v[148:149], off
	v_lshl_add_u64 v[148:149], v[138:139], 0, s[64:65]
	s_add_i32 m0, s13, 0x1a000
	s_add_i32 s26, s13, 0x8000
	global_load_lds_dwordx4 v[148:149], off
	v_lshl_add_u64 v[148:149], v[140:141], 0, s[62:63]
	s_mov_b32 m0, s26
	s_add_i32 s27, s13, 0xa000
	global_load_lds_dwordx4 v[148:149], off
	v_lshl_add_u64 v[140:141], v[140:141], 0, s[64:65]
	s_mov_b32 m0, s27
	v_and_b32_e32 v149, 15, v0
	global_load_lds_dwordx4 v[140:141], off
	v_lshl_add_u64 v[140:141], v[138:139], 0, s[66:67]
	s_add_i32 m0, s13, 0x1c000
	v_lshl_add_u64 v[138:139], v[138:139], 0, s[68:69]
	global_load_lds_dwordx4 v[140:141], off
	s_add_i32 m0, s13, 0x1e000
	v_lshl_or_b32 v156, s1, 6, v149
	global_load_lds_dwordx4 v[138:139], off
	v_lshlrev_b32_e32 v155, 6, v156
	v_and_b32_e32 v157, 48, v0
	s_movk_i32 s3, 0x3c0
	v_lshlrev_b32_e32 v159, 2, v0
	s_and_b32 s28, s2, 3
	v_and_or_b32 v158, v155, s3, v157
	s_lshl_b32 s1, s1, 13
	v_and_b32_e32 v159, 32, v159
	v_bitop3_b32 v158, v158, s1, v159 bitop3:0xde
	v_lshl_or_b32 v149, v149, 6, v157
	s_lshl_b32 s1, s28, 12
	v_bitop3_b32 v162, v149, s1, v159 bitop3:0xde
	s_lshl_b32 s1, s2, 1
	v_and_b32_e32 v148, 63, v0
	v_lshrrev_b32_e32 v154, 1, v0
	v_bfe_u32 v0, v0, 2, 4
	s_or_b32 s1, s1, 1
	v_lshl_or_b32 v163, s2, 5, v0
	s_lshl_b32 s2, s2, 11
	v_lshl_or_b32 v164, s1, 4, v0
	s_lshl_b32 s1, s1, 10
	s_cmpk_lt_u32 s6, 0x100
	v_cmp_gt_u32_e64 s[6:7], 16, v148
	v_and_b32_e32 v148, 48, v145
	v_lshlrev_b32_e32 v145, 15, v144
	s_mov_b64 s[8:9], 0x3ce00000
	v_and_b32_e32 v145, 0xffff0000, v145
	v_lshl_add_u64 v[138:139], v[142:143], 0, s[8:9]
	s_mov_b64 s[8:9], 0x12200000
	s_waitcnt vmcnt(0)
	v_mov_b32_e32 v149, v1
	v_readlane_b32 s3, v254, 11
	v_lshl_add_u32 v145, v146, 12, v145
	v_and_b32_e32 v144, 1, v144
	v_lshl_add_u64 v[140:141], v[142:143], 0, s[8:9]
	v_and_b32_e32 v154, 24, v154
	v_lshl_add_u64 v[142:143], v[142:143], 0, v[148:149]
	s_mov_b64 s[8:9], 0x3c200000
	v_add_u32_e32 v0, s3, v155
	v_lshl_or_b32 v144, v144, 6, v145
	s_cselect_b64 s[14:15], -1, 0
	v_lshl_or_b32 v165, s28, 5, v154
	s_ashr_i32 s29, s21, 31
	s_ashr_i32 s30, s20, 31
	v_lshl_add_u64 v[142:143], v[142:143], 0, s[8:9]
	v_lshl_add_u32 v144, v147, 1, v144
	v_mov_b32_e32 v145, v1
	s_mov_b32 s31, 0
	v_add_u32_e32 v166, 0, v158
	v_add_u32_e32 v167, v0, v157
	s_add_i32 s34, s3, s2
	s_add_i32 s35, s3, s1
	s_barrier
	s_branch .LBB0_165

.LBB0_165:
	s_add_i32 s31, s31, 1
	s_mul_i32 s1, s31, s29
	s_mul_hi_u32 s2, s31, s21
	s_add_i32 s1, s2, s1
	s_mul_i32 s2, s31, s21
	s_add_u32 s2, s2, s20
	s_addc_u32 s3, s1, s30
	v_mov_b64_e32 v[146:147], 0xa00
	v_cmp_lt_i64_e64 s[8:9], s[2:3], v[146:147]
	v_mov_b64_e32 v[146:147], 0x9ff
	v_cmp_gt_i64_e32 vcc, s[2:3], v[146:147]
	s_cbranch_vccnz .LBB0_167
	s_ashr_i32 s1, s2, 31
	s_lshr_b32 s1, s1, 29
	s_add_i32 s1, s2, s1
	s_ashr_i32 s3, s1, 3
	s_and_b32 s1, s1, -8
	s_sub_i32 s1, s2, s1
	s_cmp_lt_i32 s1, 0
	s_movk_i32 s2, 0x141
	s_cselect_b32 s2, s2, 0x140
	s_mul_i32 s1, s1, s2
	s_add_i32 s1, s1, s3
	s_ashr_i32 s2, s1, 31
	s_lshr_b32 s2, s2, 25
	s_add_i32 s2, s1, s2
	s_ashr_i32 s3, s2, 7
	s_lshl_b32 s3, s3, 3
	s_and_b32 s2, s2, 0xffffff80
	s_sub_i32 s1, s1, s2
	s_lshr_b32 s16, s1, 3
	s_and_b32 s1, s1, 7
	s_add_i32 s18, s3, s1
.LBB0_167:
	s_lshl_b32 s0, s0, 8
	v_add_u32_e32 v158, s0, v163
	s_ashr_i32 s19, s18, 31
	v_ashrrev_i32_e32 v159, 31, v158
	s_lshl_b64 s[2:3], s[18:19], 20
	s_ashr_i32 s17, s16, 31
	v_lshlrev_b64 v[160:161], 6, v[158:159]
	v_add_u32_e32 v158, s0, v164
	v_lshl_add_u64 v[146:147], v[130:131], 0, s[2:3]
	s_lshl_b64 s[2:3], s[16:17], 20
	v_ashrrev_i32_e32 v159, 31, v158
	v_lshl_add_u64 v[148:149], v[132:133], 0, s[2:3]
	v_lshlrev_b64 v[158:159], 6, v[158:159]
	v_cndmask_b32_e64 v155, v153, v147, s[8:9]
	v_cndmask_b32_e64 v0, v152, v146, s[8:9]
	v_cndmask_b32_e64 v157, v151, v149, s[8:9]
	v_cndmask_b32_e64 v154, v150, v148, s[8:9]
	v_lshl_add_u64 v[158:159], v[142:143], 0, v[158:159]
	v_lshl_add_u64 v[160:161], v[142:143], 0, v[160:161]
	v_lshl_add_u64 v[152:153], v[152:153], 0, s[66:67]
	v_lshl_add_u64 v[150:151], v[150:151], 0, s[72:73]
	s_mov_b32 s1, -2
	s_mov_b64 vcc, 0
	s_add_i32 s2, 0, 0x10000
	s_add_i32 s3, 0, 0x14000
	v_lshl_add_u64 v[168:169], v[152:153], 0, s[74:75]
	v_add_u32_e32 v180, s2, v162
	v_add_u32_e32 v196, s3, v162
	v_cndmask_b32_e32 v205, v169, v155, vcc
	v_cndmask_b32_e32 v204, v168, v0, vcc
	ds_read_b128 v[168:171], v180
	ds_read_b128 v[172:175], v180 offset:1024
	ds_read_b128 v[176:179], v180 offset:2048
	ds_read_b128 v[180:183], v180 offset:3072
	ds_read_b128 v[184:187], v196
	ds_read_b128 v[188:191], v196 offset:1024
	ds_read_b128 v[192:195], v196 offset:2048
	ds_read_b128 v[196:199], v196 offset:3072
	v_cndmask_b32_e32 v207, v151, v157, vcc
	v_cndmask_b32_e32 v206, v150, v154, vcc
	v_lshl_add_u64 v[238:239], v[152:153], 0, v[144:145]
	s_add_i32 m0, s13, 0xc000
	ds_read_b128 v[200:203], v166
	ds_read_b128 v[210:213], v166 offset:1024
	ds_read_b128 v[214:217], v166 offset:2048
	ds_read_b128 v[218:221], v166 offset:3072
	ds_read_b128 v[222:225], v166 offset:4096
	ds_read_b128 v[226:229], v166 offset:5120
	ds_read_b128 v[230:233], v166 offset:6144
	ds_read_b128 v[234:237], v166 offset:7168
	global_load_lds_dwordx4 v[238:239], off
	v_lshl_add_u64 v[238:239], v[238:239], 0, s[52:53]
	s_add_i32 m0, s13, 0xe000
	s_nop 0
	global_load_lds_dwordx4 v[238:239], off
	s_waitcnt vmcnt(24)
	s_waitcnt lgkmcnt(0)
	s_barrier
	s_setprio 1
	s_waitcnt lgkmcnt(0)
	v_mfma_f32_16x16x32_bf16 v[122:125], v[168:171], v[200:203], 0
	v_mfma_f32_16x16x32_bf16 v[126:129], v[176:179], v[200:203], 0
	v_mfma_f32_16x16x32_bf16 v[106:109], v[168:171], v[214:217], 0
	v_mfma_f32_16x16x32_bf16 v[110:113], v[176:179], v[214:217], 0
	v_mfma_f32_16x16x32_bf16 v[90:93], v[168:171], v[222:225], 0
	v_mfma_f32_16x16x32_bf16 v[94:97], v[176:179], v[222:225], 0
	v_mfma_f32_16x16x32_bf16 v[74:77], v[168:171], v[230:233], 0
	v_mfma_f32_16x16x32_bf16 v[78:81], v[176:179], v[230:233], 0
	v_mfma_f32_16x16x32_bf16 v[122:125], v[172:175], v[210:213], v[122:125]
	v_mfma_f32_16x16x32_bf16 v[126:129], v[180:183], v[210:213], v[126:129]
	v_mfma_f32_16x16x32_bf16 v[106:109], v[172:175], v[218:221], v[106:109]
	v_mfma_f32_16x16x32_bf16 v[110:113], v[180:183], v[218:221], v[110:113]
	v_mfma_f32_16x16x32_bf16 v[90:93], v[172:175], v[226:229], v[90:93]
	v_mfma_f32_16x16x32_bf16 v[94:97], v[180:183], v[226:229], v[94:97]
	v_mfma_f32_16x16x32_bf16 v[74:77], v[172:175], v[234:237], v[74:77]
	v_mfma_f32_16x16x32_bf16 v[78:81], v[180:183], v[234:237], v[78:81]
	s_setprio 0
	s_setprio 1
	v_mfma_f32_16x16x32_bf16 v[114:117], v[184:187], v[200:203], 0
	v_mfma_f32_16x16x32_bf16 v[118:121], v[192:195], v[200:203], 0
	v_mfma_f32_16x16x32_bf16 v[98:101], v[184:187], v[214:217], 0
	v_mfma_f32_16x16x32_bf16 v[102:105], v[192:195], v[214:217], 0
	v_mfma_f32_16x16x32_bf16 v[82:85], v[184:187], v[222:225], 0
	v_mfma_f32_16x16x32_bf16 v[86:89], v[192:195], v[222:225], 0
	v_mfma_f32_16x16x32_bf16 v[66:69], v[184:187], v[230:233], 0
	v_mfma_f32_16x16x32_bf16 v[70:73], v[192:195], v[230:233], 0
	v_mfma_f32_16x16x32_bf16 v[114:117], v[188:191], v[210:213], v[114:117]
	v_mfma_f32_16x16x32_bf16 v[118:121], v[196:199], v[210:213], v[118:121]
	v_mfma_f32_16x16x32_bf16 v[98:101], v[188:191], v[218:221], v[98:101]
	v_mfma_f32_16x16x32_bf16 v[102:105], v[196:199], v[218:221], v[102:105]
	v_mfma_f32_16x16x32_bf16 v[82:85], v[188:191], v[226:229], v[82:85]
	v_mfma_f32_16x16x32_bf16 v[86:89], v[196:199], v[226:229], v[86:89]
	v_mfma_f32_16x16x32_bf16 v[66:69], v[188:191], v[234:237], v[66:69]
	v_mfma_f32_16x16x32_bf16 v[70:73], v[196:199], v[234:237], v[70:73]
	s_setprio 0
	s_barrier
	s_add_i32 s2, s2, s22
	v_lshl_add_u64 v[206:207], v[206:207], 0, v[136:137]
	s_mov_b32 m0, s2
	ds_read_b128 v[200:203], v166 offset:16384
	ds_read_b128 v[210:213], v166 offset:17408
	ds_read_b128 v[214:217], v166 offset:18432
	ds_read_b128 v[218:221], v166 offset:19456
	ds_read_b128 v[222:225], v166 offset:20480
	ds_read_b128 v[226:229], v166 offset:21504
	ds_read_b128 v[230:233], v166 offset:22528
	ds_read_b128 v[234:237], v166 offset:23552
	global_load_lds_dwordx4 v[206:207], off
	v_lshl_add_u64 v[238:239], v[206:207], 0, s[52:53]
	s_add_i32 m0, s2, 0x2000
	s_add_i32 s2, s3, s22
	global_load_lds_dwordx4 v[238:239], off
	v_lshl_add_u64 v[238:239], v[206:207], 0, s[54:55]
	s_mov_b32 m0, s2
	v_lshl_add_u64 v[204:205], v[204:205], 0, v[134:135]
	global_load_lds_dwordx4 v[238:239], off
	v_lshl_add_u64 v[238:239], v[206:207], 0, s[56:57]
	s_add_i32 m0, s2, 0x2000
	s_nop 0
	global_load_lds_dwordx4 v[238:239], off
	s_mov_b32 m0, s13
	v_lshl_add_u64 v[238:239], v[204:205], 0, s[52:53]
	global_load_lds_dwordx4 v[204:205], off
	s_mov_b32 m0, s23
	s_nop 0
	global_load_lds_dwordx4 v[238:239], off
	s_waitcnt vmcnt(24)
	s_waitcnt lgkmcnt(0)
	s_barrier
	s_setprio 1
	s_waitcnt lgkmcnt(0)
	v_mfma_f32_16x16x32_bf16 v[58:61], v[168:171], v[200:203], 0
	v_mfma_f32_16x16x32_bf16 v[62:65], v[176:179], v[200:203], 0
	v_mfma_f32_16x16x32_bf16 v[42:45], v[168:171], v[214:217], 0
	v_mfma_f32_16x16x32_bf16 v[46:49], v[176:179], v[214:217], 0
	v_mfma_f32_16x16x32_bf16 v[26:29], v[168:171], v[222:225], 0
	v_mfma_f32_16x16x32_bf16 v[30:33], v[176:179], v[222:225], 0
	v_mfma_f32_16x16x32_bf16 v[10:13], v[168:171], v[230:233], 0
	v_mfma_f32_16x16x32_bf16 v[14:17], v[176:179], v[230:233], 0
	v_mfma_f32_16x16x32_bf16 v[58:61], v[172:175], v[210:213], v[58:61]
	v_mfma_f32_16x16x32_bf16 v[62:65], v[180:183], v[210:213], v[62:65]
	v_mfma_f32_16x16x32_bf16 v[42:45], v[172:175], v[218:221], v[42:45]
	v_mfma_f32_16x16x32_bf16 v[46:49], v[180:183], v[218:221], v[46:49]
	v_mfma_f32_16x16x32_bf16 v[26:29], v[172:175], v[226:229], v[26:29]
	v_mfma_f32_16x16x32_bf16 v[30:33], v[180:183], v[226:229], v[30:33]
	v_mfma_f32_16x16x32_bf16 v[10:13], v[172:175], v[234:237], v[10:13]
	v_mfma_f32_16x16x32_bf16 v[14:17], v[180:183], v[234:237], v[14:17]
	s_setprio 0
	s_setprio 1
	v_mfma_f32_16x16x32_bf16 v[50:53], v[184:187], v[200:203], 0
	v_mfma_f32_16x16x32_bf16 v[54:57], v[192:195], v[200:203], 0
	v_mfma_f32_16x16x32_bf16 v[34:37], v[184:187], v[214:217], 0
	v_mfma_f32_16x16x32_bf16 v[38:41], v[192:195], v[214:217], 0
	v_mfma_f32_16x16x32_bf16 v[18:21], v[184:187], v[222:225], 0
	v_mfma_f32_16x16x32_bf16 v[22:25], v[192:195], v[222:225], 0
	v_mfma_f32_16x16x32_bf16 v[2:5], v[184:187], v[230:233], 0
	v_mfma_f32_16x16x32_bf16 v[6:9], v[192:195], v[230:233], 0
	v_mfma_f32_16x16x32_bf16 v[50:53], v[188:191], v[210:213], v[50:53]
	v_mfma_f32_16x16x32_bf16 v[54:57], v[196:199], v[210:213], v[54:57]
	v_mfma_f32_16x16x32_bf16 v[34:37], v[188:191], v[218:221], v[34:37]
	v_mfma_f32_16x16x32_bf16 v[38:41], v[196:199], v[218:221], v[38:41]
	v_mfma_f32_16x16x32_bf16 v[18:21], v[188:191], v[226:229], v[18:21]
	v_mfma_f32_16x16x32_bf16 v[22:25], v[196:199], v[226:229], v[22:25]
	v_mfma_f32_16x16x32_bf16 v[2:5], v[188:191], v[234:237], v[2:5]
	v_mfma_f32_16x16x32_bf16 v[6:9], v[196:199], v[234:237], v[6:9]
	s_setprio 0
	s_barrier
	s_add_i32 s2, 0, 0x18000
	s_add_i32 s3, 0, 0x1c000
	v_add_u32_e32 v180, s2, v162
	v_add_u32_e32 v196, s3, v162
	ds_read_b128 v[168:171], v180
	ds_read_b128 v[172:175], v180 offset:1024
	ds_read_b128 v[176:179], v180 offset:2048
	ds_read_b128 v[180:183], v180 offset:3072
	ds_read_b128 v[184:187], v196
	ds_read_b128 v[188:191], v196 offset:1024
	ds_read_b128 v[192:195], v196 offset:2048
	ds_read_b128 v[196:199], v196 offset:3072
	s_mov_b32 m0, s24
	v_lshl_add_u64 v[238:239], v[204:205], 0, s[54:55]
	ds_read_b128 v[200:203], v166 offset:32768
	ds_read_b128 v[210:213], v166 offset:33792
	ds_read_b128 v[214:217], v166 offset:34816
	ds_read_b128 v[218:221], v166 offset:35840
	ds_read_b128 v[222:225], v166 offset:36864
	ds_read_b128 v[226:229], v166 offset:37888
	ds_read_b128 v[230:233], v166 offset:38912
	ds_read_b128 v[234:237], v166 offset:39936
	global_load_lds_dwordx4 v[238:239], off
	v_lshl_add_u64 v[238:239], v[204:205], 0, s[56:57]
	s_mov_b32 m0, s25
	s_nop 0
	global_load_lds_dwordx4 v[238:239], off
	s_waitcnt vmcnt(8)
	s_waitcnt lgkmcnt(0)
	s_barrier
	s_setprio 1
	s_waitcnt lgkmcnt(0)
	v_mfma_f32_16x16x32_bf16 v[122:125], v[168:171], v[200:203], v[122:125]
	v_mfma_f32_16x16x32_bf16 v[126:129], v[176:179], v[200:203], v[126:129]
	v_mfma_f32_16x16x32_bf16 v[106:109], v[168:171], v[214:217], v[106:109]
	v_mfma_f32_16x16x32_bf16 v[110:113], v[176:179], v[214:217], v[110:113]
	v_mfma_f32_16x16x32_bf16 v[90:93], v[168:171], v[222:225], v[90:93]
	v_mfma_f32_16x16x32_bf16 v[94:97], v[176:179], v[222:225], v[94:97]
	v_mfma_f32_16x16x32_bf16 v[74:77], v[168:171], v[230:233], v[74:77]
	v_mfma_f32_16x16x32_bf16 v[78:81], v[176:179], v[230:233], v[78:81]
	v_mfma_f32_16x16x32_bf16 v[122:125], v[172:175], v[210:213], v[122:125]
	v_mfma_f32_16x16x32_bf16 v[126:129], v[180:183], v[210:213], v[126:129]
	v_mfma_f32_16x16x32_bf16 v[106:109], v[172:175], v[218:221], v[106:109]
	v_mfma_f32_16x16x32_bf16 v[110:113], v[180:183], v[218:221], v[110:113]
	v_mfma_f32_16x16x32_bf16 v[90:93], v[172:175], v[226:229], v[90:93]
	v_mfma_f32_16x16x32_bf16 v[94:97], v[180:183], v[226:229], v[94:97]
	v_mfma_f32_16x16x32_bf16 v[74:77], v[172:175], v[234:237], v[74:77]
	v_mfma_f32_16x16x32_bf16 v[78:81], v[180:183], v[234:237], v[78:81]
	s_setprio 0
	s_setprio 1
	v_mfma_f32_16x16x32_bf16 v[114:117], v[184:187], v[200:203], v[114:117]
	v_mfma_f32_16x16x32_bf16 v[118:121], v[192:195], v[200:203], v[118:121]
	v_mfma_f32_16x16x32_bf16 v[98:101], v[184:187], v[214:217], v[98:101]
	v_mfma_f32_16x16x32_bf16 v[102:105], v[192:195], v[214:217], v[102:105]
	v_mfma_f32_16x16x32_bf16 v[82:85], v[184:187], v[222:225], v[82:85]
	v_mfma_f32_16x16x32_bf16 v[86:89], v[192:195], v[222:225], v[86:89]
	v_mfma_f32_16x16x32_bf16 v[66:69], v[184:187], v[230:233], v[66:69]
	v_mfma_f32_16x16x32_bf16 v[70:73], v[192:195], v[230:233], v[70:73]
	v_mfma_f32_16x16x32_bf16 v[114:117], v[188:191], v[210:213], v[114:117]
	v_mfma_f32_16x16x32_bf16 v[118:121], v[196:199], v[210:213], v[118:121]
	v_mfma_f32_16x16x32_bf16 v[98:101], v[188:191], v[218:221], v[98:101]
	v_mfma_f32_16x16x32_bf16 v[102:105], v[196:199], v[218:221], v[102:105]
	v_mfma_f32_16x16x32_bf16 v[82:85], v[188:191], v[226:229], v[82:85]
	v_mfma_f32_16x16x32_bf16 v[86:89], v[196:199], v[226:229], v[86:89]
	v_mfma_f32_16x16x32_bf16 v[66:69], v[188:191], v[234:237], v[66:69]
	v_mfma_f32_16x16x32_bf16 v[70:73], v[196:199], v[234:237], v[70:73]
	s_setprio 0
	s_barrier
	s_add_i32 s2, s2, s22
	v_lshl_add_u64 v[238:239], v[206:207], 0, s[62:63]
	s_mov_b32 m0, s2
	ds_read_b128 v[200:203], v166 offset:49152
	ds_read_b128 v[210:213], v166 offset:50176
	ds_read_b128 v[214:217], v166 offset:51200
	ds_read_b128 v[218:221], v166 offset:52224
	ds_read_b128 v[222:225], v166 offset:53248
	ds_read_b128 v[226:229], v166 offset:54272
	ds_read_b128 v[230:233], v166 offset:55296
	ds_read_b128 v[234:237], v166 offset:56320
	global_load_lds_dwordx4 v[238:239], off
	v_lshl_add_u64 v[238:239], v[206:207], 0, s[64:65]
	s_add_i32 m0, s2, 0x2000
	s_add_i32 s2, s3, s22
	global_load_lds_dwordx4 v[238:239], off
	v_lshl_add_u64 v[238:239], v[206:207], 0, s[66:67]
	s_mov_b32 m0, s2
	v_lshl_add_u64 v[206:207], v[206:207], 0, s[68:69]
	global_load_lds_dwordx4 v[238:239], off
	s_add_i32 m0, s2, 0x2000
	s_nop 0
	global_load_lds_dwordx4 v[206:207], off
	v_lshl_add_u64 v[206:207], v[204:205], 0, s[62:63]
	s_mov_b32 m0, s26
	v_lshl_add_u64 v[204:205], v[204:205], 0, s[64:65]
	global_load_lds_dwordx4 v[206:207], off
	s_mov_b32 m0, s27
	s_nop 0
	global_load_lds_dwordx4 v[204:205], off
	s_waitcnt vmcnt(8)
	s_waitcnt lgkmcnt(0)
	s_barrier
	s_setprio 1
	s_waitcnt lgkmcnt(0)
	v_mfma_f32_16x16x32_bf16 v[58:61], v[168:171], v[200:203], v[58:61]
	v_mfma_f32_16x16x32_bf16 v[62:65], v[176:179], v[200:203], v[62:65]
	v_mfma_f32_16x16x32_bf16 v[42:45], v[168:171], v[214:217], v[42:45]
	v_mfma_f32_16x16x32_bf16 v[46:49], v[176:179], v[214:217], v[46:49]
	v_mfma_f32_16x16x32_bf16 v[26:29], v[168:171], v[222:225], v[26:29]
	v_mfma_f32_16x16x32_bf16 v[30:33], v[176:179], v[222:225], v[30:33]
	v_mfma_f32_16x16x32_bf16 v[10:13], v[168:171], v[230:233], v[10:13]
	v_mfma_f32_16x16x32_bf16 v[14:17], v[176:179], v[230:233], v[14:17]
	v_mfma_f32_16x16x32_bf16 v[58:61], v[172:175], v[210:213], v[58:61]
	v_mfma_f32_16x16x32_bf16 v[62:65], v[180:183], v[210:213], v[62:65]
	v_mfma_f32_16x16x32_bf16 v[42:45], v[172:175], v[218:221], v[42:45]
	v_mfma_f32_16x16x32_bf16 v[46:49], v[180:183], v[218:221], v[46:49]
	v_mfma_f32_16x16x32_bf16 v[26:29], v[172:175], v[226:229], v[26:29]
	v_mfma_f32_16x16x32_bf16 v[30:33], v[180:183], v[226:229], v[30:33]
	v_mfma_f32_16x16x32_bf16 v[10:13], v[172:175], v[234:237], v[10:13]
	v_mfma_f32_16x16x32_bf16 v[14:17], v[180:183], v[234:237], v[14:17]
	s_setprio 0
	s_setprio 1
	v_mfma_f32_16x16x32_bf16 v[50:53], v[184:187], v[200:203], v[50:53]
	v_mfma_f32_16x16x32_bf16 v[54:57], v[192:195], v[200:203], v[54:57]
	v_mfma_f32_16x16x32_bf16 v[34:37], v[184:187], v[214:217], v[34:37]
	v_mfma_f32_16x16x32_bf16 v[38:41], v[192:195], v[214:217], v[38:41]
	v_mfma_f32_16x16x32_bf16 v[18:21], v[184:187], v[222:225], v[18:21]
	v_mfma_f32_16x16x32_bf16 v[22:25], v[192:195], v[222:225], v[22:25]
	v_mfma_f32_16x16x32_bf16 v[2:5], v[184:187], v[230:233], v[2:5]
	v_mfma_f32_16x16x32_bf16 v[6:9], v[192:195], v[230:233], v[6:9]
	v_mfma_f32_16x16x32_bf16 v[50:53], v[188:191], v[210:213], v[50:53]
	v_mfma_f32_16x16x32_bf16 v[54:57], v[196:199], v[210:213], v[54:57]
	v_mfma_f32_16x16x32_bf16 v[34:37], v[188:191], v[218:221], v[34:37]
	v_mfma_f32_16x16x32_bf16 v[38:41], v[196:199], v[218:221], v[38:41]
	v_mfma_f32_16x16x32_bf16 v[18:21], v[188:191], v[226:229], v[18:21]
	v_mfma_f32_16x16x32_bf16 v[22:25], v[196:199], v[226:229], v[22:25]
	v_mfma_f32_16x16x32_bf16 v[2:5], v[188:191], v[234:237], v[2:5]
	v_mfma_f32_16x16x32_bf16 v[6:9], v[196:199], v[234:237], v[6:9]
	s_setprio 0
	s_barrier
	s_add_i32 s1, s1, 2
	v_lshl_add_u64 v[152:153], v[152:153], 0, s[72:73]
	s_cmp_gt_u32 s1, 29
	v_lshl_add_u64 v[150:151], v[150:151], 0, s[72:73]
	s_branch .LBB0_169

.LBB0_414:
	v_lshl_add_u64 v[144:145], v[136:137], 0, s[62:63]
	s_add_i32 m0, s23, 0x18000
	s_waitcnt vmcnt(2)
	s_barrier
	global_load_lds_dwordx4 v[144:145], off
	v_lshl_add_u64 v[144:145], v[136:137], 0, s[64:65]
	s_add_i32 m0, s23, 0x1a000
	s_add_i32 s27, s23, 0x8000
	global_load_lds_dwordx4 v[144:145], off
	v_lshl_add_u64 v[144:145], v[138:139], 0, s[62:63]
	s_mov_b32 m0, s27
	s_add_i32 s28, s23, 0xa000
	global_load_lds_dwordx4 v[144:145], off
	v_lshl_add_u64 v[138:139], v[138:139], 0, s[66:67]
	s_mov_b32 m0, s28
	s_mov_b64 s[8:9], 0x8200000
	global_load_lds_dwordx4 v[138:139], off
	v_lshl_add_u64 v[138:139], v[136:137], 0, s[66:67]
	s_add_i32 m0, s23, 0x1c000
	v_lshl_add_u64 v[136:137], v[136:137], 0, s[68:69]
	global_load_lds_dwordx4 v[138:139], off
	s_add_i32 m0, s23, 0x1e000
	v_lshl_add_u64 v[202:203], v[132:133], 0, s[8:9]
	global_load_lds_dwordx4 v[136:137], off
	s_mov_b64 s[8:9], 0x3c800000
	v_lshl_add_u64 v[204:205], v[132:133], 0, s[8:9]
	v_bfe_u32 v133, v0, 4, 2
	v_and_b32_e32 v132, 15, v0
	v_lshlrev_b32_e32 v137, 4, v133
	v_lshlrev_b32_e32 v0, 2, v0
	s_and_b32 s29, s3, 3
	v_lshl_or_b32 v238, s6, 6, v132
	v_lshl_or_b32 v132, v132, 6, v137
	s_lshl_b32 s3, s6, 13
	v_and_b32_e32 v0, 32, v0
	v_bitop3_b32 v137, v132, s3, v0 bitop3:0xde
	s_lshl_b32 s3, s29, 12
	v_bitop3_b32 v239, v132, s3, v0 bitop3:0xde
	v_lshlrev_b32_e32 v0, 16, v140
	v_and_b32_e32 v0, 0xfffe0000, v0
	s_waitcnt vmcnt(0)
	v_lshl_add_u32 v0, v141, 13, v0
	v_and_b32_e32 v132, 1, v140
	v_lshlrev_b32_e32 v136, 3, v133
	s_cmpk_lt_u32 s2, 0x100
	v_lshl_or_b32 v0, v132, 6, v0
	v_lshl_or_b32 v250, s29, 5, v136
	s_cselect_b64 s[2:3], -1, 0
	s_mov_b32 s30, 0
	v_cmp_eq_u32_e64 s[6:7], 0, v133
	s_waitcnt lgkmcnt(0)
	s_ashr_i32 s31, s21, 31
	s_ashr_i32 s34, s20, 31
	v_lshl_add_u32 v210, v142, 1, v0
	v_mov_b32_e32 v211, v1
	v_add_u32_e32 v251, 0, v137
	s_barrier
	s_branch .LBB0_417

.LBB0_417:
	s_add_i32 s30, s30, 1
	s_mul_i32 s8, s30, s31
	s_mul_hi_u32 s9, s30, s21
	s_add_i32 s9, s9, s8
	s_mul_i32 s8, s30, s21
	s_add_u32 s18, s8, s20
	s_addc_u32 s19, s9, s34
	v_mov_b64_e32 v[132:133], 0x4ff
	v_cmp_gt_i64_e32 vcc, s[18:19], v[132:133]
	v_cmp_lt_i64_e64 s[8:9], s[18:19], v[242:243]
	s_cbranch_vccnz .LBB0_419
	s_ashr_i32 s10, s18, 31
	s_lshr_b32 s10, s10, 29
	s_add_i32 s10, s18, s10
	s_ashr_i32 s11, s10, 3
	s_and_b32 s10, s10, -8
	s_sub_i32 s10, s18, s10
	s_cmp_lt_i32 s10, 0
	s_movk_i32 s12, 0xa1
	s_cselect_b32 s12, s12, 0xa0
	s_mul_i32 s10, s10, s12
	s_add_i32 s10, s10, s11
	s_ashr_i32 s11, s10, 31
	s_lshr_b32 s11, s11, 26
	s_add_i32 s11, s10, s11
	s_ashr_i32 s12, s11, 5
	s_lshl_b32 s12, s12, 2
	s_andn2_b32 s11, s11, 31
	s_sub_i32 s11, s10, s11
	s_lshr_b32 s10, s11, 2
	s_and_b32 s11, s11, 3
	s_add_i32 s12, s12, s11
.LBB0_419:
	s_ashr_i32 s13, s12, 31
	s_lshl_b64 s[18:19], s[12:13], 21
	s_ashr_i32 s11, s10, 31
	v_lshl_add_u64 v[212:213], v[194:195], 0, s[18:19]
	s_lshl_b64 s[18:19], s[10:11], 20
	v_lshl_add_u64 v[214:215], v[196:197], 0, s[18:19]
	v_cndmask_b32_e64 v133, v135, v213, s[8:9]
	v_cndmask_b32_e64 v0, v134, v212, s[8:9]
	v_cndmask_b32_e64 v137, v131, v215, s[8:9]
	v_cndmask_b32_e64 v132, v130, v214, s[8:9]
	v_lshl_add_u64 v[134:135], v[134:135], 0, s[70:71]
	v_lshl_add_u64 v[130:131], v[130:131], 0, s[72:73]
	s_mov_b32 s11, -2
	s_cmp_eq_u32 s11, 28
	s_cselect_b64 vcc, -1, 0
	s_add_i32 s13, 0, 0x10000
	v_add_u32_e32 v136, s13, v239
	s_add_i32 s15, 0, 0x14000
	ds_read_b128 v[138:141], v136
	ds_read_b128 v[142:145], v136 offset:1024
	ds_read_b128 v[146:149], v136 offset:2048
	ds_read_b128 v[150:153], v136 offset:3072
	v_add_u32_e32 v136, s15, v239
	ds_read_b128 v[154:157], v136
	ds_read_b128 v[158:161], v136 offset:1024
	ds_read_b128 v[162:165], v136 offset:2048
	ds_read_b128 v[166:169], v136 offset:3072
	s_mov_b32 s18, 0xfff00080
	s_mov_b32 s19, -1
	v_lshl_add_u64 v[170:171], v[134:135], 0, s[18:19]
	v_cndmask_b32_e32 v207, v171, v133, vcc
	v_cndmask_b32_e32 v206, v170, v0, vcc
	v_cndmask_b32_e32 v225, v131, v137, vcc
	v_cndmask_b32_e32 v224, v130, v132, vcc
	v_lshl_add_u64 v[226:227], v[134:135], 0, v[210:211]
	s_add_i32 m0, s23, 0xc000
	ds_read_b128 v[170:173], v251
	ds_read_b128 v[174:177], v251 offset:1024
	ds_read_b128 v[178:181], v251 offset:2048
	ds_read_b128 v[182:185], v251 offset:3072
	ds_read_b128 v[186:189], v251 offset:4096
	ds_read_b128 v[190:193], v251 offset:5120
	ds_read_b128 v[216:219], v251 offset:6144
	ds_read_b128 v[220:223], v251 offset:7168
	global_load_lds_dwordx4 v[226:227], off
	v_lshl_add_u64 v[226:227], v[226:227], 0, s[54:55]
	s_add_i32 m0, s23, 0xe000
	s_nop 0
	global_load_lds_dwordx4 v[226:227], off
	s_waitcnt vmcnt(24)
	s_waitcnt lgkmcnt(0)
	s_barrier
	s_setprio 1
	s_waitcnt lgkmcnt(0)
	v_mfma_f32_16x16x32_bf16 v[122:125], v[138:141], v[170:173], 0
	v_mfma_f32_16x16x32_bf16 v[126:129], v[146:149], v[170:173], 0
	v_mfma_f32_16x16x32_bf16 v[110:113], v[138:141], v[178:181], 0
	v_mfma_f32_16x16x32_bf16 v[106:109], v[146:149], v[178:181], 0
	v_mfma_f32_16x16x32_bf16 v[94:97], v[138:141], v[186:189], 0
	v_mfma_f32_16x16x32_bf16 v[90:93], v[146:149], v[186:189], 0
	v_mfma_f32_16x16x32_bf16 v[78:81], v[138:141], v[216:219], 0
	v_mfma_f32_16x16x32_bf16 v[74:77], v[146:149], v[216:219], 0
	v_mfma_f32_16x16x32_bf16 v[122:125], v[142:145], v[174:177], v[122:125]
	v_mfma_f32_16x16x32_bf16 v[126:129], v[150:153], v[174:177], v[126:129]
	v_mfma_f32_16x16x32_bf16 v[110:113], v[142:145], v[182:185], v[110:113]
	v_mfma_f32_16x16x32_bf16 v[106:109], v[150:153], v[182:185], v[106:109]
	v_mfma_f32_16x16x32_bf16 v[94:97], v[142:145], v[190:193], v[94:97]
	v_mfma_f32_16x16x32_bf16 v[90:93], v[150:153], v[190:193], v[90:93]
	v_mfma_f32_16x16x32_bf16 v[78:81], v[142:145], v[220:223], v[78:81]
	v_mfma_f32_16x16x32_bf16 v[74:77], v[150:153], v[220:223], v[74:77]
	s_setprio 0
	s_setprio 1
	v_mfma_f32_16x16x32_bf16 v[118:121], v[154:157], v[170:173], 0
	v_mfma_f32_16x16x32_bf16 v[114:117], v[162:165], v[170:173], 0
	v_mfma_f32_16x16x32_bf16 v[102:105], v[154:157], v[178:181], 0
	v_mfma_f32_16x16x32_bf16 v[98:101], v[162:165], v[178:181], 0
	v_mfma_f32_16x16x32_bf16 v[86:89], v[154:157], v[186:189], 0
	v_mfma_f32_16x16x32_bf16 v[82:85], v[162:165], v[186:189], 0
	v_mfma_f32_16x16x32_bf16 v[70:73], v[154:157], v[216:219], 0
	v_mfma_f32_16x16x32_bf16 v[66:69], v[162:165], v[216:219], 0
	v_mfma_f32_16x16x32_bf16 v[118:121], v[158:161], v[174:177], v[118:121]
	v_mfma_f32_16x16x32_bf16 v[114:117], v[166:169], v[174:177], v[114:117]
	v_mfma_f32_16x16x32_bf16 v[102:105], v[158:161], v[182:185], v[102:105]
	v_mfma_f32_16x16x32_bf16 v[98:101], v[166:169], v[182:185], v[98:101]
	v_mfma_f32_16x16x32_bf16 v[86:89], v[158:161], v[190:193], v[86:89]
	v_mfma_f32_16x16x32_bf16 v[82:85], v[166:169], v[190:193], v[82:85]
	v_mfma_f32_16x16x32_bf16 v[70:73], v[158:161], v[220:223], v[70:73]
	v_mfma_f32_16x16x32_bf16 v[66:69], v[166:169], v[220:223], v[66:69]
	s_setprio 0
	s_barrier
	s_add_i32 s13, s13, s22
	v_lshl_add_u64 v[224:225], v[224:225], 0, v[200:201]
	s_mov_b32 m0, s13
	ds_read_b128 v[170:173], v251 offset:16384
	ds_read_b128 v[174:177], v251 offset:17408
	ds_read_b128 v[178:181], v251 offset:18432
	ds_read_b128 v[182:185], v251 offset:19456
	ds_read_b128 v[186:189], v251 offset:20480
	ds_read_b128 v[190:193], v251 offset:21504
	ds_read_b128 v[216:219], v251 offset:22528
	ds_read_b128 v[220:223], v251 offset:23552
	global_load_lds_dwordx4 v[224:225], off
	v_lshl_add_u64 v[226:227], v[224:225], 0, s[52:53]
	s_add_i32 m0, s13, 0x2000
	s_add_i32 s13, s15, s22
	global_load_lds_dwordx4 v[226:227], off
	v_lshl_add_u64 v[226:227], v[224:225], 0, s[54:55]
	s_mov_b32 m0, s13
	v_lshl_add_u64 v[206:207], v[206:207], 0, v[198:199]
	global_load_lds_dwordx4 v[226:227], off
	v_lshl_add_u64 v[226:227], v[224:225], 0, s[56:57]
	s_add_i32 m0, s13, 0x2000
	s_nop 0
	global_load_lds_dwordx4 v[226:227], off
	s_mov_b32 m0, s23
	v_lshl_add_u64 v[226:227], v[206:207], 0, s[54:55]
	global_load_lds_dwordx4 v[206:207], off
	s_mov_b32 m0, s24
	s_nop 0
	global_load_lds_dwordx4 v[226:227], off
	s_waitcnt vmcnt(24)
	s_waitcnt lgkmcnt(0)
	s_barrier
	s_setprio 1
	s_waitcnt lgkmcnt(0)
	v_mfma_f32_16x16x32_bf16 v[62:65], v[138:141], v[170:173], 0
	v_mfma_f32_16x16x32_bf16 v[58:61], v[146:149], v[170:173], 0
	v_mfma_f32_16x16x32_bf16 v[46:49], v[138:141], v[178:181], 0
	v_mfma_f32_16x16x32_bf16 v[42:45], v[146:149], v[178:181], 0
	v_mfma_f32_16x16x32_bf16 v[30:33], v[138:141], v[186:189], 0
	v_mfma_f32_16x16x32_bf16 v[26:29], v[146:149], v[186:189], 0
	v_mfma_f32_16x16x32_bf16 v[14:17], v[138:141], v[216:219], 0
	v_mfma_f32_16x16x32_bf16 v[10:13], v[146:149], v[216:219], 0
	v_mfma_f32_16x16x32_bf16 v[62:65], v[142:145], v[174:177], v[62:65]
	v_mfma_f32_16x16x32_bf16 v[58:61], v[150:153], v[174:177], v[58:61]
	v_mfma_f32_16x16x32_bf16 v[46:49], v[142:145], v[182:185], v[46:49]
	v_mfma_f32_16x16x32_bf16 v[42:45], v[150:153], v[182:185], v[42:45]
	v_mfma_f32_16x16x32_bf16 v[30:33], v[142:145], v[190:193], v[30:33]
	v_mfma_f32_16x16x32_bf16 v[26:29], v[150:153], v[190:193], v[26:29]
	v_mfma_f32_16x16x32_bf16 v[14:17], v[142:145], v[220:223], v[14:17]
	v_mfma_f32_16x16x32_bf16 v[10:13], v[150:153], v[220:223], v[10:13]
	s_setprio 0
	s_setprio 1
	v_mfma_f32_16x16x32_bf16 v[54:57], v[154:157], v[170:173], 0
	v_mfma_f32_16x16x32_bf16 v[50:53], v[162:165], v[170:173], 0
	v_mfma_f32_16x16x32_bf16 v[38:41], v[154:157], v[178:181], 0
	v_mfma_f32_16x16x32_bf16 v[34:37], v[162:165], v[178:181], 0
	v_mfma_f32_16x16x32_bf16 v[22:25], v[154:157], v[186:189], 0
	v_mfma_f32_16x16x32_bf16 v[18:21], v[162:165], v[186:189], 0
	v_mfma_f32_16x16x32_bf16 v[6:9], v[154:157], v[216:219], 0
	v_mfma_f32_16x16x32_bf16 v[2:5], v[162:165], v[216:219], 0
	v_mfma_f32_16x16x32_bf16 v[54:57], v[158:161], v[174:177], v[54:57]
	v_mfma_f32_16x16x32_bf16 v[50:53], v[166:169], v[174:177], v[50:53]
	v_mfma_f32_16x16x32_bf16 v[38:41], v[158:161], v[182:185], v[38:41]
	v_mfma_f32_16x16x32_bf16 v[34:37], v[166:169], v[182:185], v[34:37]
	v_mfma_f32_16x16x32_bf16 v[22:25], v[158:161], v[190:193], v[22:25]
	v_mfma_f32_16x16x32_bf16 v[18:21], v[166:169], v[190:193], v[18:21]
	v_mfma_f32_16x16x32_bf16 v[6:9], v[158:161], v[220:223], v[6:9]
	v_mfma_f32_16x16x32_bf16 v[2:5], v[166:169], v[220:223], v[2:5]
	s_setprio 0
	s_barrier
	s_add_i32 s13, 0, 0x18000
	v_add_u32_e32 v136, s13, v239
	s_add_i32 s15, 0, 0x1c000
	ds_read_b128 v[138:141], v136
	ds_read_b128 v[142:145], v136 offset:1024
	ds_read_b128 v[146:149], v136 offset:2048
	ds_read_b128 v[150:153], v136 offset:3072
	v_add_u32_e32 v136, s15, v239
	ds_read_b128 v[154:157], v136
	ds_read_b128 v[158:161], v136 offset:1024
	ds_read_b128 v[162:165], v136 offset:2048
	ds_read_b128 v[166:169], v136 offset:3072
	s_mov_b32 m0, s25
	v_lshl_add_u64 v[226:227], v[206:207], 0, s[84:85]
	ds_read_b128 v[170:173], v251 offset:32768
	ds_read_b128 v[174:177], v251 offset:33792
	ds_read_b128 v[178:181], v251 offset:34816
	ds_read_b128 v[182:185], v251 offset:35840
	ds_read_b128 v[186:189], v251 offset:36864
	ds_read_b128 v[190:193], v251 offset:37888
	ds_read_b128 v[216:219], v251 offset:38912
	ds_read_b128 v[220:223], v251 offset:39936
	global_load_lds_dwordx4 v[226:227], off
	v_lshl_add_u64 v[226:227], v[206:207], 0, s[86:87]
	s_mov_b32 m0, s26
	s_nop 0
	global_load_lds_dwordx4 v[226:227], off
	s_waitcnt vmcnt(8)
	s_waitcnt lgkmcnt(0)
	s_barrier
	s_setprio 1
	s_waitcnt lgkmcnt(0)
	v_mfma_f32_16x16x32_bf16 v[122:125], v[138:141], v[170:173], v[122:125]
	v_mfma_f32_16x16x32_bf16 v[126:129], v[146:149], v[170:173], v[126:129]
	v_mfma_f32_16x16x32_bf16 v[110:113], v[138:141], v[178:181], v[110:113]
	v_mfma_f32_16x16x32_bf16 v[106:109], v[146:149], v[178:181], v[106:109]
	v_mfma_f32_16x16x32_bf16 v[94:97], v[138:141], v[186:189], v[94:97]
	v_mfma_f32_16x16x32_bf16 v[90:93], v[146:149], v[186:189], v[90:93]
	v_mfma_f32_16x16x32_bf16 v[78:81], v[138:141], v[216:219], v[78:81]
	v_mfma_f32_16x16x32_bf16 v[74:77], v[146:149], v[216:219], v[74:77]
	v_mfma_f32_16x16x32_bf16 v[122:125], v[142:145], v[174:177], v[122:125]
	v_mfma_f32_16x16x32_bf16 v[126:129], v[150:153], v[174:177], v[126:129]
	v_mfma_f32_16x16x32_bf16 v[110:113], v[142:145], v[182:185], v[110:113]
	v_mfma_f32_16x16x32_bf16 v[106:109], v[150:153], v[182:185], v[106:109]
	v_mfma_f32_16x16x32_bf16 v[94:97], v[142:145], v[190:193], v[94:97]
	v_mfma_f32_16x16x32_bf16 v[90:93], v[150:153], v[190:193], v[90:93]
	v_mfma_f32_16x16x32_bf16 v[78:81], v[142:145], v[220:223], v[78:81]
	v_mfma_f32_16x16x32_bf16 v[74:77], v[150:153], v[220:223], v[74:77]
	s_setprio 0
	s_setprio 1
	v_mfma_f32_16x16x32_bf16 v[118:121], v[154:157], v[170:173], v[118:121]
	v_mfma_f32_16x16x32_bf16 v[114:117], v[162:165], v[170:173], v[114:117]
	v_mfma_f32_16x16x32_bf16 v[102:105], v[154:157], v[178:181], v[102:105]
	v_mfma_f32_16x16x32_bf16 v[98:101], v[162:165], v[178:181], v[98:101]
	v_mfma_f32_16x16x32_bf16 v[86:89], v[154:157], v[186:189], v[86:89]
	v_mfma_f32_16x16x32_bf16 v[82:85], v[162:165], v[186:189], v[82:85]
	v_mfma_f32_16x16x32_bf16 v[70:73], v[154:157], v[216:219], v[70:73]
	v_mfma_f32_16x16x32_bf16 v[66:69], v[162:165], v[216:219], v[66:69]
	v_mfma_f32_16x16x32_bf16 v[118:121], v[158:161], v[174:177], v[118:121]
	v_mfma_f32_16x16x32_bf16 v[114:117], v[166:169], v[174:177], v[114:117]
	v_mfma_f32_16x16x32_bf16 v[102:105], v[158:161], v[182:185], v[102:105]
	v_mfma_f32_16x16x32_bf16 v[98:101], v[166:169], v[182:185], v[98:101]
	v_mfma_f32_16x16x32_bf16 v[86:89], v[158:161], v[190:193], v[86:89]
	v_mfma_f32_16x16x32_bf16 v[82:85], v[166:169], v[190:193], v[82:85]
	v_mfma_f32_16x16x32_bf16 v[70:73], v[158:161], v[220:223], v[70:73]
	v_mfma_f32_16x16x32_bf16 v[66:69], v[166:169], v[220:223], v[66:69]
	s_setprio 0
	s_barrier
	s_add_i32 s13, s13, s22
	v_lshl_add_u64 v[226:227], v[224:225], 0, s[62:63]
	s_mov_b32 m0, s13
	ds_read_b128 v[170:173], v251 offset:49152
	ds_read_b128 v[174:177], v251 offset:50176
	ds_read_b128 v[178:181], v251 offset:51200
	ds_read_b128 v[182:185], v251 offset:52224
	ds_read_b128 v[186:189], v251 offset:53248
	ds_read_b128 v[190:193], v251 offset:54272
	ds_read_b128 v[216:219], v251 offset:55296
	ds_read_b128 v[220:223], v251 offset:56320
	global_load_lds_dwordx4 v[226:227], off
	v_lshl_add_u64 v[226:227], v[224:225], 0, s[64:65]
	s_add_i32 m0, s13, 0x2000
	s_add_i32 s13, s15, s22
	global_load_lds_dwordx4 v[226:227], off
	v_lshl_add_u64 v[226:227], v[224:225], 0, s[66:67]
	s_mov_b32 m0, s13
	v_lshl_add_u64 v[224:225], v[224:225], 0, s[68:69]
	global_load_lds_dwordx4 v[226:227], off
	s_add_i32 m0, s13, 0x2000
	s_nop 0
	global_load_lds_dwordx4 v[224:225], off
	v_lshl_add_u64 v[224:225], v[206:207], 0, s[62:63]
	s_mov_b32 m0, s27
	v_lshl_add_u64 v[206:207], v[206:207], 0, s[66:67]
	global_load_lds_dwordx4 v[224:225], off
	s_mov_b32 m0, s28
	s_nop 0
	global_load_lds_dwordx4 v[206:207], off
	s_waitcnt vmcnt(8)
	s_waitcnt lgkmcnt(0)
	s_barrier
	s_setprio 1
	s_waitcnt lgkmcnt(0)
	v_mfma_f32_16x16x32_bf16 v[62:65], v[138:141], v[170:173], v[62:65]
	v_mfma_f32_16x16x32_bf16 v[58:61], v[146:149], v[170:173], v[58:61]
	v_mfma_f32_16x16x32_bf16 v[46:49], v[138:141], v[178:181], v[46:49]
	v_mfma_f32_16x16x32_bf16 v[42:45], v[146:149], v[178:181], v[42:45]
	v_mfma_f32_16x16x32_bf16 v[30:33], v[138:141], v[186:189], v[30:33]
	v_mfma_f32_16x16x32_bf16 v[26:29], v[146:149], v[186:189], v[26:29]
	v_mfma_f32_16x16x32_bf16 v[14:17], v[138:141], v[216:219], v[14:17]
	v_mfma_f32_16x16x32_bf16 v[10:13], v[146:149], v[216:219], v[10:13]
	v_mfma_f32_16x16x32_bf16 v[62:65], v[142:145], v[174:177], v[62:65]
	v_mfma_f32_16x16x32_bf16 v[58:61], v[150:153], v[174:177], v[58:61]
	v_mfma_f32_16x16x32_bf16 v[46:49], v[142:145], v[182:185], v[46:49]
	v_mfma_f32_16x16x32_bf16 v[42:45], v[150:153], v[182:185], v[42:45]
	v_mfma_f32_16x16x32_bf16 v[30:33], v[142:145], v[190:193], v[30:33]
	v_mfma_f32_16x16x32_bf16 v[26:29], v[150:153], v[190:193], v[26:29]
	v_mfma_f32_16x16x32_bf16 v[14:17], v[142:145], v[220:223], v[14:17]
	v_mfma_f32_16x16x32_bf16 v[10:13], v[150:153], v[220:223], v[10:13]
	s_setprio 0
	s_setprio 1
	v_mfma_f32_16x16x32_bf16 v[54:57], v[154:157], v[170:173], v[54:57]
	v_mfma_f32_16x16x32_bf16 v[50:53], v[162:165], v[170:173], v[50:53]
	v_mfma_f32_16x16x32_bf16 v[38:41], v[154:157], v[178:181], v[38:41]
	v_mfma_f32_16x16x32_bf16 v[34:37], v[162:165], v[178:181], v[34:37]
	v_mfma_f32_16x16x32_bf16 v[22:25], v[154:157], v[186:189], v[22:25]
	v_mfma_f32_16x16x32_bf16 v[18:21], v[162:165], v[186:189], v[18:21]
	v_mfma_f32_16x16x32_bf16 v[6:9], v[154:157], v[216:219], v[6:9]
	v_mfma_f32_16x16x32_bf16 v[2:5], v[162:165], v[216:219], v[2:5]
	v_mfma_f32_16x16x32_bf16 v[54:57], v[158:161], v[174:177], v[54:57]
	v_mfma_f32_16x16x32_bf16 v[50:53], v[166:169], v[174:177], v[50:53]
	v_mfma_f32_16x16x32_bf16 v[38:41], v[158:161], v[182:185], v[38:41]
	v_mfma_f32_16x16x32_bf16 v[34:37], v[166:169], v[182:185], v[34:37]
	v_mfma_f32_16x16x32_bf16 v[22:25], v[158:161], v[190:193], v[22:25]
	v_mfma_f32_16x16x32_bf16 v[18:21], v[166:169], v[190:193], v[18:21]
	v_mfma_f32_16x16x32_bf16 v[6:9], v[158:161], v[220:223], v[6:9]
	v_mfma_f32_16x16x32_bf16 v[2:5], v[166:169], v[220:223], v[2:5]
	s_setprio 0
	s_barrier
	s_add_i32 s11, s11, 2
	v_lshl_add_u64 v[134:135], v[134:135], 0, s[72:73]
	s_cmp_gt_u32 s11, 29
	v_lshl_add_u64 v[130:131], v[130:131], 0, s[72:73]

.LBB0_499:
	v_lshl_add_u64 v[148:149], v[138:139], 0, s[62:63]
	s_add_i32 m0, s21, 0x18000
	s_waitcnt vmcnt(2)
	s_barrier
	global_load_lds_dwordx4 v[148:149], off
	v_lshl_add_u64 v[148:149], v[138:139], 0, s[64:65]
	s_add_i32 m0, s21, 0x1a000
	s_add_i32 s25, s21, 0x8000
	global_load_lds_dwordx4 v[148:149], off
	v_lshl_add_u64 v[148:149], v[140:141], 0, s[62:63]
	s_mov_b32 m0, s25
	s_add_i32 s26, s21, 0xa000
	global_load_lds_dwordx4 v[148:149], off
	v_lshl_add_u64 v[140:141], v[140:141], 0, s[64:65]
	s_mov_b32 m0, s26
	s_mov_b64 s[6:7], 0x3ce00000
	global_load_lds_dwordx4 v[140:141], off
	v_lshl_add_u64 v[140:141], v[138:139], 0, s[66:67]
	s_add_i32 m0, s21, 0x1c000
	v_lshl_add_u64 v[138:139], v[138:139], 0, s[68:69]
	global_load_lds_dwordx4 v[140:141], off
	s_add_i32 m0, s21, 0x1e000
	v_and_b32_e32 v149, 15, v0
	global_load_lds_dwordx4 v[138:139], off
	v_lshl_add_u64 v[138:139], v[142:143], 0, s[6:7]
	s_mov_b64 s[6:7], 0x12200000
	v_lshl_or_b32 v156, s3, 6, v149
	v_lshl_add_u64 v[140:141], v[142:143], 0, s[6:7]
	v_lshlrev_b32_e32 v155, 6, v156
	v_and_b32_e32 v157, 48, v0
	s_movk_i32 s6, 0x3c0
	v_lshlrev_b32_e32 v159, 2, v0
	s_and_b32 s27, s5, 3
	v_and_or_b32 v158, v155, s6, v157
	s_lshl_b32 s3, s3, 13
	v_and_b32_e32 v159, 32, v159
	v_bitop3_b32 v158, v158, s3, v159 bitop3:0xde
	v_lshl_or_b32 v149, v149, 6, v157
	s_lshl_b32 s3, s27, 12
	v_bitop3_b32 v162, v149, s3, v159 bitop3:0xde
	s_lshl_b32 s3, s5, 1
	v_and_b32_e32 v148, 63, v0
	v_lshrrev_b32_e32 v154, 1, v0
	v_bfe_u32 v0, v0, 2, 4
	s_or_b32 s3, s3, 1
	s_lshl_b32 s6, s5, 11
	v_lshl_or_b32 v164, s3, 4, v0
	s_lshl_b32 s3, s3, 10
	v_lshl_or_b32 v163, s5, 5, v0
	s_cmpk_lt_u32 s4, 0x100
	v_cmp_gt_u32_e64 s[4:5], 16, v148
	v_and_b32_e32 v148, 48, v145
	v_lshlrev_b32_e32 v145, 15, v144
	v_and_b32_e32 v145, 0xffff0000, v145
	s_waitcnt vmcnt(0)
	v_mov_b32_e32 v149, v1
	v_readlane_b32 s7, v254, 11
	v_lshl_add_u32 v145, v146, 12, v145
	v_and_b32_e32 v144, 1, v144
	v_and_b32_e32 v154, 24, v154
	v_lshl_add_u64 v[142:143], v[142:143], 0, v[148:149]
	s_mov_b64 s[12:13], 0x3c200000
	v_add_u32_e32 v0, s7, v155
	v_lshl_or_b32 v144, v144, 6, v145
	s_cselect_b64 s[10:11], -1, 0
	v_lshl_or_b32 v165, s27, 5, v154
	s_ashr_i32 s28, s19, 31
	s_ashr_i32 s29, s18, 31
	v_lshl_add_u64 v[142:143], v[142:143], 0, s[12:13]
	v_lshl_add_u32 v144, v147, 1, v144
	v_mov_b32_e32 v145, v1
	s_mov_b32 s30, 0
	v_add_u32_e32 v166, 0, v158
	v_add_u32_e32 v167, v0, v157
	s_add_i32 s31, s7, s6
	s_add_i32 s34, s7, s3
	s_barrier
	s_branch .LBB0_502

.LBB0_502:
	s_add_i32 s30, s30, 1
	s_mul_i32 s3, s30, s28
	s_mul_hi_u32 s6, s30, s19
	s_add_i32 s6, s6, s3
	s_mul_i32 s3, s30, s19
	s_add_u32 s16, s3, s18
	s_addc_u32 s17, s6, s29
	v_mov_b64_e32 v[146:147], 0xf00
	v_cmp_lt_i64_e64 s[6:7], s[16:17], v[146:147]
	v_mov_b64_e32 v[146:147], 0xeff
	v_cmp_gt_i64_e32 vcc, s[16:17], v[146:147]
	s_cbranch_vccnz .LBB0_504
	s_ashr_i32 s3, s16, 31
	s_lshr_b32 s3, s3, 29
	s_add_i32 s3, s16, s3
	s_ashr_i32 s9, s3, 3
	s_and_b32 s3, s3, -8
	s_sub_i32 s3, s16, s3
	s_cmp_lt_i32 s3, 0
	s_movk_i32 s12, 0x1e1
	s_cselect_b32 s12, s12, 0x1e0
	s_mul_i32 s3, s3, s12
	s_add_i32 s3, s3, s9
	s_mul_hi_i32 s9, s3, 0x2aaaaaab
	s_lshr_b32 s12, s9, 31
	s_ashr_i32 s9, s9, 5
	s_add_i32 s9, s9, s12
	s_lshl_b32 s13, s9, 3
	s_mulk_i32 s9, 0xc0
	s_sub_i32 s3, s3, s9
	s_lshr_b32 s12, s3, 3
	s_and_b32 s3, s3, 7
	s_add_i32 s14, s13, s3
.LBB0_504:
	s_lshl_b32 s3, s8, 8
	v_add_u32_e32 v158, s3, v163
	s_ashr_i32 s15, s14, 31
	v_ashrrev_i32_e32 v159, 31, v158
	s_lshl_b64 s[16:17], s[14:15], 20
	s_ashr_i32 s13, s12, 31
	v_lshlrev_b64 v[160:161], 6, v[158:159]
	v_add_u32_e32 v158, s3, v164
	v_lshl_add_u64 v[146:147], v[130:131], 0, s[16:17]
	s_lshl_b64 s[16:17], s[12:13], 20
	v_ashrrev_i32_e32 v159, 31, v158
	v_lshl_add_u64 v[148:149], v[132:133], 0, s[16:17]
	v_lshlrev_b64 v[158:159], 6, v[158:159]
	v_cndmask_b32_e64 v155, v153, v147, s[6:7]
	v_cndmask_b32_e64 v0, v152, v146, s[6:7]
	v_cndmask_b32_e64 v157, v151, v149, s[6:7]
	v_cndmask_b32_e64 v154, v150, v148, s[6:7]
	v_lshl_add_u64 v[158:159], v[142:143], 0, v[158:159]
	v_lshl_add_u64 v[160:161], v[142:143], 0, v[160:161]
	v_lshl_add_u64 v[152:153], v[152:153], 0, s[66:67]
	v_lshl_add_u64 v[150:151], v[150:151], 0, s[72:73]
	s_mov_b32 s8, -2
	s_mov_b64 vcc, 0
	s_add_i32 s9, 0, 0x10000
	s_add_i32 s13, 0, 0x14000
	v_lshl_add_u64 v[168:169], v[152:153], 0, s[74:75]
	v_add_u32_e32 v180, s9, v162
	v_add_u32_e32 v196, s13, v162
	v_cndmask_b32_e32 v205, v169, v155, vcc
	v_cndmask_b32_e32 v204, v168, v0, vcc
	ds_read_b128 v[168:171], v180
	ds_read_b128 v[172:175], v180 offset:1024
	ds_read_b128 v[176:179], v180 offset:2048
	ds_read_b128 v[180:183], v180 offset:3072
	ds_read_b128 v[184:187], v196
	ds_read_b128 v[188:191], v196 offset:1024
	ds_read_b128 v[192:195], v196 offset:2048
	ds_read_b128 v[196:199], v196 offset:3072
	v_cndmask_b32_e32 v239, v151, v157, vcc
	v_cndmask_b32_e32 v238, v150, v154, vcc
	v_lshl_add_u64 v[250:251], v[152:153], 0, v[144:145]
	s_add_i32 m0, s21, 0xc000
	ds_read_b128 v[200:203], v166
	ds_read_b128 v[210:213], v166 offset:1024
	ds_read_b128 v[214:217], v166 offset:2048
	ds_read_b128 v[218:221], v166 offset:3072
	ds_read_b128 v[222:225], v166 offset:4096
	ds_read_b128 v[226:229], v166 offset:5120
	ds_read_b128 v[230:233], v166 offset:6144
	ds_read_b128 v[234:237], v166 offset:7168
	global_load_lds_dwordx4 v[250:251], off
	v_lshl_add_u64 v[250:251], v[250:251], 0, s[52:53]
	s_add_i32 m0, s21, 0xe000
	s_nop 0
	global_load_lds_dwordx4 v[250:251], off
	s_waitcnt vmcnt(24)
	s_waitcnt lgkmcnt(0)
	s_barrier
	s_setprio 1
	s_waitcnt lgkmcnt(0)
	v_mfma_f32_16x16x32_bf16 v[126:129], v[168:171], v[200:203], 0
	v_mfma_f32_16x16x32_bf16 v[122:125], v[176:179], v[200:203], 0
	v_mfma_f32_16x16x32_bf16 v[110:113], v[168:171], v[214:217], 0
	v_mfma_f32_16x16x32_bf16 v[106:109], v[176:179], v[214:217], 0
	v_mfma_f32_16x16x32_bf16 v[94:97], v[168:171], v[222:225], 0
	v_mfma_f32_16x16x32_bf16 v[90:93], v[176:179], v[222:225], 0
	v_mfma_f32_16x16x32_bf16 v[78:81], v[168:171], v[230:233], 0
	v_mfma_f32_16x16x32_bf16 v[74:77], v[176:179], v[230:233], 0
	v_mfma_f32_16x16x32_bf16 v[126:129], v[172:175], v[210:213], v[126:129]
	v_mfma_f32_16x16x32_bf16 v[122:125], v[180:183], v[210:213], v[122:125]
	v_mfma_f32_16x16x32_bf16 v[110:113], v[172:175], v[218:221], v[110:113]
	v_mfma_f32_16x16x32_bf16 v[106:109], v[180:183], v[218:221], v[106:109]
	v_mfma_f32_16x16x32_bf16 v[94:97], v[172:175], v[226:229], v[94:97]
	v_mfma_f32_16x16x32_bf16 v[90:93], v[180:183], v[226:229], v[90:93]
	v_mfma_f32_16x16x32_bf16 v[78:81], v[172:175], v[234:237], v[78:81]
	v_mfma_f32_16x16x32_bf16 v[74:77], v[180:183], v[234:237], v[74:77]
	s_setprio 0
	s_setprio 1
	v_mfma_f32_16x16x32_bf16 v[118:121], v[184:187], v[200:203], 0
	v_mfma_f32_16x16x32_bf16 v[114:117], v[192:195], v[200:203], 0
	v_mfma_f32_16x16x32_bf16 v[102:105], v[184:187], v[214:217], 0
	v_mfma_f32_16x16x32_bf16 v[98:101], v[192:195], v[214:217], 0
	v_mfma_f32_16x16x32_bf16 v[86:89], v[184:187], v[222:225], 0
	v_mfma_f32_16x16x32_bf16 v[82:85], v[192:195], v[222:225], 0
	v_mfma_f32_16x16x32_bf16 v[70:73], v[184:187], v[230:233], 0
	v_mfma_f32_16x16x32_bf16 v[66:69], v[192:195], v[230:233], 0
	v_mfma_f32_16x16x32_bf16 v[118:121], v[188:191], v[210:213], v[118:121]
	v_mfma_f32_16x16x32_bf16 v[114:117], v[196:199], v[210:213], v[114:117]
	v_mfma_f32_16x16x32_bf16 v[102:105], v[188:191], v[218:221], v[102:105]
	v_mfma_f32_16x16x32_bf16 v[98:101], v[196:199], v[218:221], v[98:101]
	v_mfma_f32_16x16x32_bf16 v[86:89], v[188:191], v[226:229], v[86:89]
	v_mfma_f32_16x16x32_bf16 v[82:85], v[196:199], v[226:229], v[82:85]
	v_mfma_f32_16x16x32_bf16 v[70:73], v[188:191], v[234:237], v[70:73]
	v_mfma_f32_16x16x32_bf16 v[66:69], v[196:199], v[234:237], v[66:69]
	s_setprio 0
	s_barrier
	s_add_i32 s9, s9, s20
	v_lshl_add_u64 v[238:239], v[238:239], 0, v[136:137]
	s_mov_b32 m0, s9
	ds_read_b128 v[200:203], v166 offset:16384
	ds_read_b128 v[210:213], v166 offset:17408
	ds_read_b128 v[214:217], v166 offset:18432
	ds_read_b128 v[218:221], v166 offset:19456
	ds_read_b128 v[222:225], v166 offset:20480
	ds_read_b128 v[226:229], v166 offset:21504
	ds_read_b128 v[230:233], v166 offset:22528
	ds_read_b128 v[234:237], v166 offset:23552
	global_load_lds_dwordx4 v[238:239], off
	v_lshl_add_u64 v[250:251], v[238:239], 0, s[52:53]
	s_add_i32 m0, s9, 0x2000
	s_add_i32 s9, s13, s20
	global_load_lds_dwordx4 v[250:251], off
	v_lshl_add_u64 v[250:251], v[238:239], 0, s[54:55]
	s_mov_b32 m0, s9
	v_lshl_add_u64 v[204:205], v[204:205], 0, v[134:135]
	global_load_lds_dwordx4 v[250:251], off
	v_lshl_add_u64 v[250:251], v[238:239], 0, s[56:57]
	s_add_i32 m0, s9, 0x2000
	s_nop 0
	global_load_lds_dwordx4 v[250:251], off
	s_mov_b32 m0, s21
	v_lshl_add_u64 v[250:251], v[204:205], 0, s[52:53]
	global_load_lds_dwordx4 v[204:205], off
	s_mov_b32 m0, s22
	s_nop 0
	global_load_lds_dwordx4 v[250:251], off
	s_waitcnt vmcnt(24)
	s_waitcnt lgkmcnt(0)
	s_barrier
	s_setprio 1
	s_waitcnt lgkmcnt(0)
	v_mfma_f32_16x16x32_bf16 v[62:65], v[168:171], v[200:203], 0
	v_mfma_f32_16x16x32_bf16 v[58:61], v[176:179], v[200:203], 0
	v_mfma_f32_16x16x32_bf16 v[46:49], v[168:171], v[214:217], 0
	v_mfma_f32_16x16x32_bf16 v[42:45], v[176:179], v[214:217], 0
	v_mfma_f32_16x16x32_bf16 v[30:33], v[168:171], v[222:225], 0
	v_mfma_f32_16x16x32_bf16 v[26:29], v[176:179], v[222:225], 0
	v_mfma_f32_16x16x32_bf16 v[10:13], v[168:171], v[230:233], 0
	v_mfma_f32_16x16x32_bf16 v[6:9], v[176:179], v[230:233], 0
	v_mfma_f32_16x16x32_bf16 v[62:65], v[172:175], v[210:213], v[62:65]
	v_mfma_f32_16x16x32_bf16 v[58:61], v[180:183], v[210:213], v[58:61]
	v_mfma_f32_16x16x32_bf16 v[46:49], v[172:175], v[218:221], v[46:49]
	v_mfma_f32_16x16x32_bf16 v[42:45], v[180:183], v[218:221], v[42:45]
	v_mfma_f32_16x16x32_bf16 v[30:33], v[172:175], v[226:229], v[30:33]
	v_mfma_f32_16x16x32_bf16 v[26:29], v[180:183], v[226:229], v[26:29]
	v_mfma_f32_16x16x32_bf16 v[10:13], v[172:175], v[234:237], v[10:13]
	v_mfma_f32_16x16x32_bf16 v[6:9], v[180:183], v[234:237], v[6:9]
	s_setprio 0
	s_setprio 1
	v_mfma_f32_16x16x32_bf16 v[54:57], v[184:187], v[200:203], 0
	v_mfma_f32_16x16x32_bf16 v[50:53], v[192:195], v[200:203], 0
	v_mfma_f32_16x16x32_bf16 v[38:41], v[184:187], v[214:217], 0
	v_mfma_f32_16x16x32_bf16 v[34:37], v[192:195], v[214:217], 0
	v_mfma_f32_16x16x32_bf16 v[22:25], v[184:187], v[222:225], 0
	v_mfma_f32_16x16x32_bf16 v[18:21], v[192:195], v[222:225], 0
	v_mfma_f32_16x16x32_bf16 v[2:5], v[184:187], v[230:233], 0
	v_mfma_f32_16x16x32_bf16 v[14:17], v[192:195], v[230:233], 0
	v_mfma_f32_16x16x32_bf16 v[54:57], v[188:191], v[210:213], v[54:57]
	v_mfma_f32_16x16x32_bf16 v[50:53], v[196:199], v[210:213], v[50:53]
	v_mfma_f32_16x16x32_bf16 v[38:41], v[188:191], v[218:221], v[38:41]
	v_mfma_f32_16x16x32_bf16 v[34:37], v[196:199], v[218:221], v[34:37]
	v_mfma_f32_16x16x32_bf16 v[22:25], v[188:191], v[226:229], v[22:25]
	v_mfma_f32_16x16x32_bf16 v[18:21], v[196:199], v[226:229], v[18:21]
	v_mfma_f32_16x16x32_bf16 v[2:5], v[188:191], v[234:237], v[2:5]
	v_mfma_f32_16x16x32_bf16 v[14:17], v[196:199], v[234:237], v[14:17]
	s_setprio 0
	s_barrier
	s_add_i32 s9, 0, 0x18000
	s_add_i32 s13, 0, 0x1c000
	v_add_u32_e32 v180, s9, v162
	v_add_u32_e32 v196, s13, v162
	ds_read_b128 v[168:171], v180
	ds_read_b128 v[172:175], v180 offset:1024
	ds_read_b128 v[176:179], v180 offset:2048
	ds_read_b128 v[180:183], v180 offset:3072
	ds_read_b128 v[184:187], v196
	ds_read_b128 v[188:191], v196 offset:1024
	ds_read_b128 v[192:195], v196 offset:2048
	ds_read_b128 v[196:199], v196 offset:3072
	s_mov_b32 m0, s23
	v_lshl_add_u64 v[250:251], v[204:205], 0, s[54:55]
	ds_read_b128 v[200:203], v166 offset:32768
	ds_read_b128 v[210:213], v166 offset:33792
	ds_read_b128 v[214:217], v166 offset:34816
	ds_read_b128 v[218:221], v166 offset:35840
	ds_read_b128 v[222:225], v166 offset:36864
	ds_read_b128 v[226:229], v166 offset:37888
	ds_read_b128 v[230:233], v166 offset:38912
	ds_read_b128 v[234:237], v166 offset:39936
	global_load_lds_dwordx4 v[250:251], off
	v_lshl_add_u64 v[250:251], v[204:205], 0, s[56:57]
	s_mov_b32 m0, s24
	s_nop 0
	global_load_lds_dwordx4 v[250:251], off
	s_waitcnt vmcnt(8)
	s_waitcnt lgkmcnt(0)
	s_barrier
	s_setprio 1
	s_waitcnt lgkmcnt(0)
	v_mfma_f32_16x16x32_bf16 v[126:129], v[168:171], v[200:203], v[126:129]
	v_mfma_f32_16x16x32_bf16 v[122:125], v[176:179], v[200:203], v[122:125]
	v_mfma_f32_16x16x32_bf16 v[110:113], v[168:171], v[214:217], v[110:113]
	v_mfma_f32_16x16x32_bf16 v[106:109], v[176:179], v[214:217], v[106:109]
	v_mfma_f32_16x16x32_bf16 v[94:97], v[168:171], v[222:225], v[94:97]
	v_mfma_f32_16x16x32_bf16 v[90:93], v[176:179], v[222:225], v[90:93]
	v_mfma_f32_16x16x32_bf16 v[78:81], v[168:171], v[230:233], v[78:81]
	v_mfma_f32_16x16x32_bf16 v[74:77], v[176:179], v[230:233], v[74:77]
	v_mfma_f32_16x16x32_bf16 v[126:129], v[172:175], v[210:213], v[126:129]
	v_mfma_f32_16x16x32_bf16 v[122:125], v[180:183], v[210:213], v[122:125]
	v_mfma_f32_16x16x32_bf16 v[110:113], v[172:175], v[218:221], v[110:113]
	v_mfma_f32_16x16x32_bf16 v[106:109], v[180:183], v[218:221], v[106:109]
	v_mfma_f32_16x16x32_bf16 v[94:97], v[172:175], v[226:229], v[94:97]
	v_mfma_f32_16x16x32_bf16 v[90:93], v[180:183], v[226:229], v[90:93]
	v_mfma_f32_16x16x32_bf16 v[78:81], v[172:175], v[234:237], v[78:81]
	v_mfma_f32_16x16x32_bf16 v[74:77], v[180:183], v[234:237], v[74:77]
	s_setprio 0
	s_setprio 1
	v_mfma_f32_16x16x32_bf16 v[118:121], v[184:187], v[200:203], v[118:121]
	v_mfma_f32_16x16x32_bf16 v[114:117], v[192:195], v[200:203], v[114:117]
	v_mfma_f32_16x16x32_bf16 v[102:105], v[184:187], v[214:217], v[102:105]
	v_mfma_f32_16x16x32_bf16 v[98:101], v[192:195], v[214:217], v[98:101]
	v_mfma_f32_16x16x32_bf16 v[86:89], v[184:187], v[222:225], v[86:89]
	v_mfma_f32_16x16x32_bf16 v[82:85], v[192:195], v[222:225], v[82:85]
	v_mfma_f32_16x16x32_bf16 v[70:73], v[184:187], v[230:233], v[70:73]
	v_mfma_f32_16x16x32_bf16 v[66:69], v[192:195], v[230:233], v[66:69]
	v_mfma_f32_16x16x32_bf16 v[118:121], v[188:191], v[210:213], v[118:121]
	v_mfma_f32_16x16x32_bf16 v[114:117], v[196:199], v[210:213], v[114:117]
	v_mfma_f32_16x16x32_bf16 v[102:105], v[188:191], v[218:221], v[102:105]
	v_mfma_f32_16x16x32_bf16 v[98:101], v[196:199], v[218:221], v[98:101]
	v_mfma_f32_16x16x32_bf16 v[86:89], v[188:191], v[226:229], v[86:89]
	v_mfma_f32_16x16x32_bf16 v[82:85], v[196:199], v[226:229], v[82:85]
	v_mfma_f32_16x16x32_bf16 v[70:73], v[188:191], v[234:237], v[70:73]
	v_mfma_f32_16x16x32_bf16 v[66:69], v[196:199], v[234:237], v[66:69]
	s_setprio 0
	s_barrier
	s_add_i32 s9, s9, s20
	v_lshl_add_u64 v[250:251], v[238:239], 0, s[62:63]
	s_mov_b32 m0, s9
	ds_read_b128 v[200:203], v166 offset:49152
	ds_read_b128 v[210:213], v166 offset:50176
	ds_read_b128 v[214:217], v166 offset:51200
	ds_read_b128 v[218:221], v166 offset:52224
	ds_read_b128 v[222:225], v166 offset:53248
	ds_read_b128 v[226:229], v166 offset:54272
	ds_read_b128 v[230:233], v166 offset:55296
	ds_read_b128 v[234:237], v166 offset:56320
	global_load_lds_dwordx4 v[250:251], off
	v_lshl_add_u64 v[250:251], v[238:239], 0, s[64:65]
	s_add_i32 m0, s9, 0x2000
	s_add_i32 s9, s13, s20
	global_load_lds_dwordx4 v[250:251], off
	v_lshl_add_u64 v[250:251], v[238:239], 0, s[66:67]
	s_mov_b32 m0, s9
	v_lshl_add_u64 v[238:239], v[238:239], 0, s[68:69]
	global_load_lds_dwordx4 v[250:251], off
	s_add_i32 m0, s9, 0x2000
	s_nop 0
	global_load_lds_dwordx4 v[238:239], off
	v_lshl_add_u64 v[238:239], v[204:205], 0, s[62:63]
	s_mov_b32 m0, s25
	v_lshl_add_u64 v[204:205], v[204:205], 0, s[64:65]
	global_load_lds_dwordx4 v[238:239], off
	s_mov_b32 m0, s26
	s_nop 0
	global_load_lds_dwordx4 v[204:205], off
	s_waitcnt vmcnt(8)
	s_waitcnt lgkmcnt(0)
	s_barrier
	s_setprio 1
	s_waitcnt lgkmcnt(0)
	v_mfma_f32_16x16x32_bf16 v[62:65], v[168:171], v[200:203], v[62:65]
	v_mfma_f32_16x16x32_bf16 v[58:61], v[176:179], v[200:203], v[58:61]
	v_mfma_f32_16x16x32_bf16 v[46:49], v[168:171], v[214:217], v[46:49]
	v_mfma_f32_16x16x32_bf16 v[42:45], v[176:179], v[214:217], v[42:45]
	v_mfma_f32_16x16x32_bf16 v[30:33], v[168:171], v[222:225], v[30:33]
	v_mfma_f32_16x16x32_bf16 v[26:29], v[176:179], v[222:225], v[26:29]
	v_mfma_f32_16x16x32_bf16 v[10:13], v[168:171], v[230:233], v[10:13]
	v_mfma_f32_16x16x32_bf16 v[6:9], v[176:179], v[230:233], v[6:9]
	v_mfma_f32_16x16x32_bf16 v[62:65], v[172:175], v[210:213], v[62:65]
	v_mfma_f32_16x16x32_bf16 v[58:61], v[180:183], v[210:213], v[58:61]
	v_mfma_f32_16x16x32_bf16 v[46:49], v[172:175], v[218:221], v[46:49]
	v_mfma_f32_16x16x32_bf16 v[42:45], v[180:183], v[218:221], v[42:45]
	v_mfma_f32_16x16x32_bf16 v[30:33], v[172:175], v[226:229], v[30:33]
	v_mfma_f32_16x16x32_bf16 v[26:29], v[180:183], v[226:229], v[26:29]
	v_mfma_f32_16x16x32_bf16 v[10:13], v[172:175], v[234:237], v[10:13]
	v_mfma_f32_16x16x32_bf16 v[6:9], v[180:183], v[234:237], v[6:9]
	s_setprio 0
	s_setprio 1
	v_mfma_f32_16x16x32_bf16 v[54:57], v[184:187], v[200:203], v[54:57]
	v_mfma_f32_16x16x32_bf16 v[50:53], v[192:195], v[200:203], v[50:53]
	v_mfma_f32_16x16x32_bf16 v[38:41], v[184:187], v[214:217], v[38:41]
	v_mfma_f32_16x16x32_bf16 v[34:37], v[192:195], v[214:217], v[34:37]
	v_mfma_f32_16x16x32_bf16 v[22:25], v[184:187], v[222:225], v[22:25]
	v_mfma_f32_16x16x32_bf16 v[18:21], v[192:195], v[222:225], v[18:21]
	v_mfma_f32_16x16x32_bf16 v[2:5], v[184:187], v[230:233], v[2:5]
	v_mfma_f32_16x16x32_bf16 v[14:17], v[192:195], v[230:233], v[14:17]
	v_mfma_f32_16x16x32_bf16 v[54:57], v[188:191], v[210:213], v[54:57]
	v_mfma_f32_16x16x32_bf16 v[50:53], v[196:199], v[210:213], v[50:53]
	v_mfma_f32_16x16x32_bf16 v[38:41], v[188:191], v[218:221], v[38:41]
	v_mfma_f32_16x16x32_bf16 v[34:37], v[196:199], v[218:221], v[34:37]
	v_mfma_f32_16x16x32_bf16 v[22:25], v[188:191], v[226:229], v[22:25]
	v_mfma_f32_16x16x32_bf16 v[18:21], v[196:199], v[226:229], v[18:21]
	v_mfma_f32_16x16x32_bf16 v[2:5], v[188:191], v[234:237], v[2:5]
	v_mfma_f32_16x16x32_bf16 v[14:17], v[196:199], v[234:237], v[14:17]
	s_setprio 0
	s_barrier
	s_add_i32 s8, s8, 2
	v_lshl_add_u64 v[152:153], v[152:153], 0, s[72:73]
	s_cmp_gt_u32 s8, 29
	v_lshl_add_u64 v[150:151], v[150:151], 0, s[72:73]
	s_branch .LBB0_506

.LBB0_1075:
	v_lshl_add_u64 v[144:145], v[136:137], 0, s[62:63]
	s_add_i32 m0, s17, 0x18000
	s_waitcnt vmcnt(2)
	s_barrier
	global_load_lds_dwordx4 v[144:145], off
	v_lshl_add_u64 v[144:145], v[136:137], 0, s[64:65]
	s_add_i32 m0, s17, 0x1a000
	s_add_i32 s21, s17, 0x8000
	global_load_lds_dwordx4 v[144:145], off
	v_lshl_add_u64 v[144:145], v[138:139], 0, s[62:63]
	s_mov_b32 m0, s21
	s_add_i32 s22, s17, 0xa000
	global_load_lds_dwordx4 v[144:145], off
	v_lshl_add_u64 v[138:139], v[138:139], 0, s[58:59]
	s_mov_b32 m0, s22
	s_mov_b64 s[6:7], 0x8200000
	global_load_lds_dwordx4 v[138:139], off
	v_lshl_add_u64 v[138:139], v[136:137], 0, s[66:67]
	s_add_i32 m0, s17, 0x1c000
	v_lshl_add_u64 v[136:137], v[136:137], 0, s[68:69]
	global_load_lds_dwordx4 v[138:139], off
	s_add_i32 m0, s17, 0x1e000
	v_lshl_add_u64 v[202:203], v[134:135], 0, s[6:7]
	global_load_lds_dwordx4 v[136:137], off
	s_mov_b64 s[6:7], 0x3c800000
	v_lshl_add_u64 v[204:205], v[134:135], 0, s[6:7]
	v_bfe_u32 v135, v0, 4, 2
	v_and_b32_e32 v134, 15, v0
	v_lshlrev_b32_e32 v137, 4, v135
	v_lshlrev_b32_e32 v0, 2, v0
	s_and_b32 s23, s3, 3
	v_lshl_or_b32 v238, s4, 6, v134
	v_lshl_or_b32 v134, v134, 6, v137
	s_lshl_b32 s3, s4, 13
	v_and_b32_e32 v0, 32, v0
	v_bitop3_b32 v137, v134, s3, v0 bitop3:0xde
	s_lshl_b32 s3, s23, 12
	s_movk_i32 s6, 0xc00
	v_bitop3_b32 v239, v134, s3, v0 bitop3:0xde
	v_lshrrev_b32_e32 v134, 1, v140
	v_mul_lo_u32 v0, v142, s6
	s_mov_b32 s6, 0xc000
	v_lshlrev_b32_e32 v136, 3, v135
	s_waitcnt vmcnt(0)
	v_cmp_eq_u32_e64 s[4:5], 0, v135
	v_mad_u64_u32 v[134:135], s[6:7], v134, s6, v[0:1]
	s_cmpk_lt_u32 s2, 0x100
	v_or_b32_e32 v0, v134, v141
	v_lshl_or_b32 v250, s23, 5, v136
	s_cselect_b64 s[2:3], -1, 0
	s_mov_b32 s24, 0
	s_waitcnt lgkmcnt(0)
	s_ashr_i32 s25, s15, 31
	s_ashr_i32 s26, s14, 31
	v_add_lshl_u32 v210, v0, v143, 1
	v_mov_b32_e32 v211, v1
	v_add_u32_e32 v251, 0, v137
	s_barrier
	s_branch .LBB0_1078

.LBB0_1078:
	s_add_i32 s24, s24, 1
	s_mul_i32 s6, s24, s25
	s_mul_hi_u32 s7, s24, s15
	s_add_i32 s7, s7, s6
	s_mul_i32 s6, s24, s15
	s_add_u32 s6, s6, s14
	s_addc_u32 s7, s7, s26
	v_mov_b64_e32 v[134:135], 0x4ff
	v_cmp_gt_i64_e32 vcc, s[6:7], v[134:135]
	v_cmp_lt_i64_e64 s[8:9], s[6:7], v[242:243]
	s_cbranch_vccnz .LBB0_1080
	s_ashr_i32 s7, s6, 31
	s_lshr_b32 s7, s7, 29
	s_add_i32 s7, s6, s7
	s_ashr_i32 s10, s7, 3
	s_and_b32 s7, s7, -8
	s_sub_i32 s6, s6, s7
	s_cmp_lt_i32 s6, 0
	s_movk_i32 s7, 0xa1
	s_cselect_b32 s7, s7, 0xa0
	s_mul_i32 s6, s6, s7
	s_add_i32 s6, s6, s10
	s_ashr_i32 s7, s6, 31
	s_lshr_b32 s7, s7, 26
	s_add_i32 s7, s6, s7
	s_ashr_i32 s10, s7, 5
	s_lshl_b32 s11, s10, 2
	s_andn2_b32 s7, s7, 31
	s_sub_i32 s6, s6, s7
	s_lshr_b32 s10, s6, 2
	s_and_b32 s6, s6, 3
	s_add_i32 s27, s11, s6

.LBB0_1082:
	s_ashr_i32 s11, s10, 31
	s_lshl_b64 s[30:31], s[10:11], 20
	v_lshl_add_u64 v[214:215], v[196:197], 0, s[30:31]
	v_cndmask_b32_e64 v135, v131, v215, s[8:9]
	v_cndmask_b32_e64 v0, v130, v214, s[8:9]
	v_lshl_add_u64 v[132:133], v[132:133], 0, s[68:69]
	v_lshl_add_u64 v[130:131], v[130:131], 0, s[72:73]
	s_mov_b32 s8, -2
	s_cmp_eq_u32 s8, 28
	s_cselect_b64 vcc, -1, 0
	s_add_i32 s9, 0, 0x10000
	v_add_u32_e32 v134, s9, v239
	s_add_i32 s11, 0, 0x14000
	ds_read_b128 v[136:139], v134
	ds_read_b128 v[140:143], v134 offset:1024
	ds_read_b128 v[144:147], v134 offset:2048
	ds_read_b128 v[148:151], v134 offset:3072
	v_add_u32_e32 v134, s11, v239
	ds_read_b128 v[152:155], v134
	ds_read_b128 v[156:159], v134 offset:1024
	ds_read_b128 v[160:163], v134 offset:2048
	ds_read_b128 v[164:167], v134 offset:3072
	s_mov_b32 s30, 0xfff40080
	s_mov_b32 s31, -1
	v_lshl_add_u64 v[168:169], v[132:133], 0, s[30:31]
	v_cndmask_b32_e32 v193, v169, v213, vcc
	v_cndmask_b32_e32 v192, v168, v212, vcc
	v_cndmask_b32_e32 v225, v131, v135, vcc
	v_cndmask_b32_e32 v224, v130, v0, vcc
	v_lshl_add_u64 v[226:227], v[132:133], 0, v[210:211]
	s_add_i32 m0, s17, 0xc000
	ds_read_b128 v[168:171], v251
	ds_read_b128 v[172:175], v251 offset:1024
	ds_read_b128 v[176:179], v251 offset:2048
	ds_read_b128 v[180:183], v251 offset:3072
	ds_read_b128 v[184:187], v251 offset:4096
	ds_read_b128 v[188:191], v251 offset:5120
	ds_read_b128 v[216:219], v251 offset:6144
	ds_read_b128 v[220:223], v251 offset:7168
	global_load_lds_dwordx4 v[226:227], off
	v_lshl_add_u64 v[226:227], v[226:227], 0, s[90:91]
	s_add_i32 m0, s17, 0xe000
	s_nop 0
	global_load_lds_dwordx4 v[226:227], off
	s_waitcnt vmcnt(24)
	s_waitcnt lgkmcnt(0)
	s_barrier
	s_setprio 1
	s_waitcnt lgkmcnt(0)
	v_mfma_f32_16x16x32_bf16 v[122:125], v[136:139], v[168:171], 0
	v_mfma_f32_16x16x32_bf16 v[126:129], v[144:147], v[168:171], 0
	v_mfma_f32_16x16x32_bf16 v[110:113], v[136:139], v[176:179], 0
	v_mfma_f32_16x16x32_bf16 v[106:109], v[144:147], v[176:179], 0
	v_mfma_f32_16x16x32_bf16 v[94:97], v[136:139], v[184:187], 0
	v_mfma_f32_16x16x32_bf16 v[90:93], v[144:147], v[184:187], 0
	v_mfma_f32_16x16x32_bf16 v[78:81], v[136:139], v[216:219], 0
	v_mfma_f32_16x16x32_bf16 v[74:77], v[144:147], v[216:219], 0
	v_mfma_f32_16x16x32_bf16 v[122:125], v[140:143], v[172:175], v[122:125]
	v_mfma_f32_16x16x32_bf16 v[126:129], v[148:151], v[172:175], v[126:129]
	v_mfma_f32_16x16x32_bf16 v[110:113], v[140:143], v[180:183], v[110:113]
	v_mfma_f32_16x16x32_bf16 v[106:109], v[148:151], v[180:183], v[106:109]
	v_mfma_f32_16x16x32_bf16 v[94:97], v[140:143], v[188:191], v[94:97]
	v_mfma_f32_16x16x32_bf16 v[90:93], v[148:151], v[188:191], v[90:93]
	v_mfma_f32_16x16x32_bf16 v[78:81], v[140:143], v[220:223], v[78:81]
	v_mfma_f32_16x16x32_bf16 v[74:77], v[148:151], v[220:223], v[74:77]
	s_setprio 0
	s_setprio 1
	v_mfma_f32_16x16x32_bf16 v[118:121], v[152:155], v[168:171], 0
	v_mfma_f32_16x16x32_bf16 v[114:117], v[160:163], v[168:171], 0
	v_mfma_f32_16x16x32_bf16 v[102:105], v[152:155], v[176:179], 0
	v_mfma_f32_16x16x32_bf16 v[98:101], v[160:163], v[176:179], 0
	v_mfma_f32_16x16x32_bf16 v[86:89], v[152:155], v[184:187], 0
	v_mfma_f32_16x16x32_bf16 v[82:85], v[160:163], v[184:187], 0
	v_mfma_f32_16x16x32_bf16 v[70:73], v[152:155], v[216:219], 0
	v_mfma_f32_16x16x32_bf16 v[66:69], v[160:163], v[216:219], 0
	v_mfma_f32_16x16x32_bf16 v[118:121], v[156:159], v[172:175], v[118:121]
	v_mfma_f32_16x16x32_bf16 v[114:117], v[164:167], v[172:175], v[114:117]
	v_mfma_f32_16x16x32_bf16 v[102:105], v[156:159], v[180:183], v[102:105]
	v_mfma_f32_16x16x32_bf16 v[98:101], v[164:167], v[180:183], v[98:101]
	v_mfma_f32_16x16x32_bf16 v[86:89], v[156:159], v[188:191], v[86:89]
	v_mfma_f32_16x16x32_bf16 v[82:85], v[164:167], v[188:191], v[82:85]
	v_mfma_f32_16x16x32_bf16 v[70:73], v[156:159], v[220:223], v[70:73]
	v_mfma_f32_16x16x32_bf16 v[66:69], v[164:167], v[220:223], v[66:69]
	s_setprio 0
	s_barrier
	s_add_i32 s9, s9, s16
	v_lshl_add_u64 v[224:225], v[224:225], 0, v[200:201]
	s_mov_b32 m0, s9
	ds_read_b128 v[168:171], v251 offset:16384
	ds_read_b128 v[172:175], v251 offset:17408
	ds_read_b128 v[176:179], v251 offset:18432
	ds_read_b128 v[180:183], v251 offset:19456
	ds_read_b128 v[184:187], v251 offset:20480
	ds_read_b128 v[188:191], v251 offset:21504
	ds_read_b128 v[216:219], v251 offset:22528
	ds_read_b128 v[220:223], v251 offset:23552
	global_load_lds_dwordx4 v[224:225], off
	v_lshl_add_u64 v[226:227], v[224:225], 0, s[52:53]
	s_add_i32 m0, s9, 0x2000
	s_add_i32 s9, s11, s16
	global_load_lds_dwordx4 v[226:227], off
	v_lshl_add_u64 v[226:227], v[224:225], 0, s[54:55]
	s_mov_b32 m0, s9
	v_lshl_add_u64 v[192:193], v[192:193], 0, v[198:199]
	global_load_lds_dwordx4 v[226:227], off
	v_lshl_add_u64 v[226:227], v[224:225], 0, s[56:57]
	s_add_i32 m0, s9, 0x2000
	s_nop 0
	global_load_lds_dwordx4 v[226:227], off
	s_mov_b32 m0, s17
	v_lshl_add_u64 v[226:227], v[192:193], 0, s[90:91]
	global_load_lds_dwordx4 v[192:193], off
	s_mov_b32 m0, s18
	s_nop 0
	global_load_lds_dwordx4 v[226:227], off
	s_waitcnt vmcnt(24)
	s_waitcnt lgkmcnt(0)
	s_barrier
	s_setprio 1
	s_waitcnt lgkmcnt(0)
	v_mfma_f32_16x16x32_bf16 v[62:65], v[136:139], v[168:171], 0
	v_mfma_f32_16x16x32_bf16 v[58:61], v[144:147], v[168:171], 0
	v_mfma_f32_16x16x32_bf16 v[46:49], v[136:139], v[176:179], 0
	v_mfma_f32_16x16x32_bf16 v[42:45], v[144:147], v[176:179], 0
	v_mfma_f32_16x16x32_bf16 v[30:33], v[136:139], v[184:187], 0
	v_mfma_f32_16x16x32_bf16 v[26:29], v[144:147], v[184:187], 0
	v_mfma_f32_16x16x32_bf16 v[14:17], v[136:139], v[216:219], 0
	v_mfma_f32_16x16x32_bf16 v[10:13], v[144:147], v[216:219], 0
	v_mfma_f32_16x16x32_bf16 v[62:65], v[140:143], v[172:175], v[62:65]
	v_mfma_f32_16x16x32_bf16 v[58:61], v[148:151], v[172:175], v[58:61]
	v_mfma_f32_16x16x32_bf16 v[46:49], v[140:143], v[180:183], v[46:49]
	v_mfma_f32_16x16x32_bf16 v[42:45], v[148:151], v[180:183], v[42:45]
	v_mfma_f32_16x16x32_bf16 v[30:33], v[140:143], v[188:191], v[30:33]
	v_mfma_f32_16x16x32_bf16 v[26:29], v[148:151], v[188:191], v[26:29]
	v_mfma_f32_16x16x32_bf16 v[14:17], v[140:143], v[220:223], v[14:17]
	v_mfma_f32_16x16x32_bf16 v[10:13], v[148:151], v[220:223], v[10:13]
	s_setprio 0
	s_setprio 1
	v_mfma_f32_16x16x32_bf16 v[54:57], v[152:155], v[168:171], 0
	v_mfma_f32_16x16x32_bf16 v[50:53], v[160:163], v[168:171], 0
	v_mfma_f32_16x16x32_bf16 v[38:41], v[152:155], v[176:179], 0
	v_mfma_f32_16x16x32_bf16 v[34:37], v[160:163], v[176:179], 0
	v_mfma_f32_16x16x32_bf16 v[22:25], v[152:155], v[184:187], 0
	v_mfma_f32_16x16x32_bf16 v[18:21], v[160:163], v[184:187], 0
	v_mfma_f32_16x16x32_bf16 v[6:9], v[152:155], v[216:219], 0
	v_mfma_f32_16x16x32_bf16 v[2:5], v[160:163], v[216:219], 0
	v_mfma_f32_16x16x32_bf16 v[54:57], v[156:159], v[172:175], v[54:57]
	v_mfma_f32_16x16x32_bf16 v[50:53], v[164:167], v[172:175], v[50:53]
	v_mfma_f32_16x16x32_bf16 v[38:41], v[156:159], v[180:183], v[38:41]
	v_mfma_f32_16x16x32_bf16 v[34:37], v[164:167], v[180:183], v[34:37]
	v_mfma_f32_16x16x32_bf16 v[22:25], v[156:159], v[188:191], v[22:25]
	v_mfma_f32_16x16x32_bf16 v[18:21], v[164:167], v[188:191], v[18:21]
	v_mfma_f32_16x16x32_bf16 v[6:9], v[156:159], v[220:223], v[6:9]
	v_mfma_f32_16x16x32_bf16 v[2:5], v[164:167], v[220:223], v[2:5]
	s_setprio 0
	s_barrier
	s_add_i32 s9, 0, 0x18000
	v_add_u32_e32 v134, s9, v239
	s_add_i32 s11, 0, 0x1c000
	ds_read_b128 v[136:139], v134
	ds_read_b128 v[140:143], v134 offset:1024
	ds_read_b128 v[144:147], v134 offset:2048
	ds_read_b128 v[148:151], v134 offset:3072
	v_add_u32_e32 v134, s11, v239
	ds_read_b128 v[152:155], v134
	ds_read_b128 v[156:159], v134 offset:1024
	ds_read_b128 v[160:163], v134 offset:2048
	ds_read_b128 v[164:167], v134 offset:3072
	s_mov_b32 m0, s19
	v_lshl_add_u64 v[226:227], v[192:193], 0, s[56:57]
	ds_read_b128 v[168:171], v251 offset:32768
	ds_read_b128 v[172:175], v251 offset:33792
	ds_read_b128 v[176:179], v251 offset:34816
	ds_read_b128 v[180:183], v251 offset:35840
	ds_read_b128 v[184:187], v251 offset:36864
	ds_read_b128 v[188:191], v251 offset:37888
	ds_read_b128 v[216:219], v251 offset:38912
	ds_read_b128 v[220:223], v251 offset:39936
	global_load_lds_dwordx4 v[226:227], off
	v_lshl_add_u64 v[226:227], v[192:193], 0, s[78:79]
	s_mov_b32 m0, s20
	s_nop 0
	global_load_lds_dwordx4 v[226:227], off
	s_waitcnt vmcnt(8)
	s_waitcnt lgkmcnt(0)
	s_barrier
	s_setprio 1
	s_waitcnt lgkmcnt(0)
	v_mfma_f32_16x16x32_bf16 v[122:125], v[136:139], v[168:171], v[122:125]
	v_mfma_f32_16x16x32_bf16 v[126:129], v[144:147], v[168:171], v[126:129]
	v_mfma_f32_16x16x32_bf16 v[110:113], v[136:139], v[176:179], v[110:113]
	v_mfma_f32_16x16x32_bf16 v[106:109], v[144:147], v[176:179], v[106:109]
	v_mfma_f32_16x16x32_bf16 v[94:97], v[136:139], v[184:187], v[94:97]
	v_mfma_f32_16x16x32_bf16 v[90:93], v[144:147], v[184:187], v[90:93]
	v_mfma_f32_16x16x32_bf16 v[78:81], v[136:139], v[216:219], v[78:81]
	v_mfma_f32_16x16x32_bf16 v[74:77], v[144:147], v[216:219], v[74:77]
	v_mfma_f32_16x16x32_bf16 v[122:125], v[140:143], v[172:175], v[122:125]
	v_mfma_f32_16x16x32_bf16 v[126:129], v[148:151], v[172:175], v[126:129]
	v_mfma_f32_16x16x32_bf16 v[110:113], v[140:143], v[180:183], v[110:113]
	v_mfma_f32_16x16x32_bf16 v[106:109], v[148:151], v[180:183], v[106:109]
	v_mfma_f32_16x16x32_bf16 v[94:97], v[140:143], v[188:191], v[94:97]
	v_mfma_f32_16x16x32_bf16 v[90:93], v[148:151], v[188:191], v[90:93]
	v_mfma_f32_16x16x32_bf16 v[78:81], v[140:143], v[220:223], v[78:81]
	v_mfma_f32_16x16x32_bf16 v[74:77], v[148:151], v[220:223], v[74:77]
	s_setprio 0
	s_setprio 1
	v_mfma_f32_16x16x32_bf16 v[118:121], v[152:155], v[168:171], v[118:121]
	v_mfma_f32_16x16x32_bf16 v[114:117], v[160:163], v[168:171], v[114:117]
	v_mfma_f32_16x16x32_bf16 v[102:105], v[152:155], v[176:179], v[102:105]
	v_mfma_f32_16x16x32_bf16 v[98:101], v[160:163], v[176:179], v[98:101]
	v_mfma_f32_16x16x32_bf16 v[86:89], v[152:155], v[184:187], v[86:89]
	v_mfma_f32_16x16x32_bf16 v[82:85], v[160:163], v[184:187], v[82:85]
	v_mfma_f32_16x16x32_bf16 v[70:73], v[152:155], v[216:219], v[70:73]
	v_mfma_f32_16x16x32_bf16 v[66:69], v[160:163], v[216:219], v[66:69]
	v_mfma_f32_16x16x32_bf16 v[118:121], v[156:159], v[172:175], v[118:121]
	v_mfma_f32_16x16x32_bf16 v[114:117], v[164:167], v[172:175], v[114:117]
	v_mfma_f32_16x16x32_bf16 v[102:105], v[156:159], v[180:183], v[102:105]
	v_mfma_f32_16x16x32_bf16 v[98:101], v[164:167], v[180:183], v[98:101]
	v_mfma_f32_16x16x32_bf16 v[86:89], v[156:159], v[188:191], v[86:89]
	v_mfma_f32_16x16x32_bf16 v[82:85], v[164:167], v[188:191], v[82:85]
	v_mfma_f32_16x16x32_bf16 v[70:73], v[156:159], v[220:223], v[70:73]
	v_mfma_f32_16x16x32_bf16 v[66:69], v[164:167], v[220:223], v[66:69]
	s_setprio 0
	s_barrier
	s_add_i32 s9, s9, s16
	v_lshl_add_u64 v[226:227], v[224:225], 0, s[62:63]
	s_mov_b32 m0, s9
	ds_read_b128 v[168:171], v251 offset:49152
	ds_read_b128 v[172:175], v251 offset:50176
	ds_read_b128 v[176:179], v251 offset:51200
	ds_read_b128 v[180:183], v251 offset:52224
	ds_read_b128 v[184:187], v251 offset:53248
	ds_read_b128 v[188:191], v251 offset:54272
	ds_read_b128 v[216:219], v251 offset:55296
	ds_read_b128 v[220:223], v251 offset:56320
	global_load_lds_dwordx4 v[226:227], off
	v_lshl_add_u64 v[226:227], v[224:225], 0, s[64:65]
	s_add_i32 m0, s9, 0x2000
	s_add_i32 s9, s11, s16
	global_load_lds_dwordx4 v[226:227], off
	v_lshl_add_u64 v[226:227], v[224:225], 0, s[66:67]
	s_mov_b32 m0, s9
	v_lshl_add_u64 v[224:225], v[224:225], 0, s[68:69]
	global_load_lds_dwordx4 v[226:227], off
	s_add_i32 m0, s9, 0x2000
	s_nop 0
	global_load_lds_dwordx4 v[224:225], off
	v_lshl_add_u64 v[224:225], v[192:193], 0, s[62:63]
	s_mov_b32 m0, s21
	v_lshl_add_u64 v[192:193], v[192:193], 0, s[58:59]
	global_load_lds_dwordx4 v[224:225], off
	s_mov_b32 m0, s22
	s_nop 0
	global_load_lds_dwordx4 v[192:193], off
	s_waitcnt vmcnt(8)
	s_waitcnt lgkmcnt(0)
	s_barrier
	s_setprio 1
	s_waitcnt lgkmcnt(0)
	v_mfma_f32_16x16x32_bf16 v[62:65], v[136:139], v[168:171], v[62:65]
	v_mfma_f32_16x16x32_bf16 v[58:61], v[144:147], v[168:171], v[58:61]
	v_mfma_f32_16x16x32_bf16 v[46:49], v[136:139], v[176:179], v[46:49]
	v_mfma_f32_16x16x32_bf16 v[42:45], v[144:147], v[176:179], v[42:45]
	v_mfma_f32_16x16x32_bf16 v[30:33], v[136:139], v[184:187], v[30:33]
	v_mfma_f32_16x16x32_bf16 v[26:29], v[144:147], v[184:187], v[26:29]
	v_mfma_f32_16x16x32_bf16 v[14:17], v[136:139], v[216:219], v[14:17]
	v_mfma_f32_16x16x32_bf16 v[10:13], v[144:147], v[216:219], v[10:13]
	v_mfma_f32_16x16x32_bf16 v[62:65], v[140:143], v[172:175], v[62:65]
	v_mfma_f32_16x16x32_bf16 v[58:61], v[148:151], v[172:175], v[58:61]
	v_mfma_f32_16x16x32_bf16 v[46:49], v[140:143], v[180:183], v[46:49]
	v_mfma_f32_16x16x32_bf16 v[42:45], v[148:151], v[180:183], v[42:45]
	v_mfma_f32_16x16x32_bf16 v[30:33], v[140:143], v[188:191], v[30:33]
	v_mfma_f32_16x16x32_bf16 v[26:29], v[148:151], v[188:191], v[26:29]
	v_mfma_f32_16x16x32_bf16 v[14:17], v[140:143], v[220:223], v[14:17]
	v_mfma_f32_16x16x32_bf16 v[10:13], v[148:151], v[220:223], v[10:13]
	s_setprio 0
	s_setprio 1
	v_mfma_f32_16x16x32_bf16 v[54:57], v[152:155], v[168:171], v[54:57]
	v_mfma_f32_16x16x32_bf16 v[50:53], v[160:163], v[168:171], v[50:53]
	v_mfma_f32_16x16x32_bf16 v[38:41], v[152:155], v[176:179], v[38:41]
	v_mfma_f32_16x16x32_bf16 v[34:37], v[160:163], v[176:179], v[34:37]
	v_mfma_f32_16x16x32_bf16 v[22:25], v[152:155], v[184:187], v[22:25]
	v_mfma_f32_16x16x32_bf16 v[18:21], v[160:163], v[184:187], v[18:21]
	v_mfma_f32_16x16x32_bf16 v[6:9], v[152:155], v[216:219], v[6:9]
	v_mfma_f32_16x16x32_bf16 v[2:5], v[160:163], v[216:219], v[2:5]
	v_mfma_f32_16x16x32_bf16 v[54:57], v[156:159], v[172:175], v[54:57]
	v_mfma_f32_16x16x32_bf16 v[50:53], v[164:167], v[172:175], v[50:53]
	v_mfma_f32_16x16x32_bf16 v[38:41], v[156:159], v[180:183], v[38:41]
	v_mfma_f32_16x16x32_bf16 v[34:37], v[164:167], v[180:183], v[34:37]
	v_mfma_f32_16x16x32_bf16 v[22:25], v[156:159], v[188:191], v[22:25]
	v_mfma_f32_16x16x32_bf16 v[18:21], v[164:167], v[188:191], v[18:21]
	v_mfma_f32_16x16x32_bf16 v[6:9], v[156:159], v[220:223], v[6:9]
	v_mfma_f32_16x16x32_bf16 v[2:5], v[164:167], v[220:223], v[2:5]
	s_setprio 0
	s_barrier
	s_add_i32 s8, s8, 2
	v_lshl_add_u64 v[132:133], v[132:133], 0, s[72:73]
	s_cmp_gt_u32 s8, 29
	v_lshl_add_u64 v[130:131], v[130:131], 0, s[72:73]

.LBB0_1158:
	v_lshl_add_u64 v[152:153], v[138:139], 0, s[62:63]
	s_add_i32 m0, s18, 0x18000
	s_waitcnt vmcnt(2)
	s_barrier
	global_load_lds_dwordx4 v[152:153], off
	v_lshl_add_u64 v[152:153], v[138:139], 0, s[64:65]
	s_add_i32 m0, s18, 0x1a000
	s_add_i32 s22, s18, 0x8000
	global_load_lds_dwordx4 v[152:153], off
	v_lshl_add_u64 v[152:153], v[142:143], 0, s[62:63]
	s_mov_b32 m0, s22
	s_add_i32 s23, s18, 0xa000
	global_load_lds_dwordx4 v[152:153], off
	v_lshl_add_u64 v[142:143], v[142:143], 0, s[64:65]
	s_mov_b32 m0, s23
	s_sext_i32_i16 s11, s2
	global_load_lds_dwordx4 v[142:143], off
	v_lshl_add_u64 v[142:143], v[138:139], 0, s[66:67]
	s_add_i32 m0, s18, 0x1c000
	v_lshl_add_u64 v[138:139], v[138:139], 0, s[68:69]
	global_load_lds_dwordx4 v[142:143], off
	s_add_i32 m0, s18, 0x1e000
	v_and_b32_e32 v142, 15, v0
	global_load_lds_dwordx4 v[138:139], off
	v_lshl_or_b32 v161, s5, 6, v142
	v_lshlrev_b32_e32 v153, 6, v161
	v_and_b32_e32 v154, 48, v0
	s_movk_i32 s2, 0x3c0
	v_lshlrev_b32_e32 v155, 2, v0
	v_and_or_b32 v143, v153, s2, v154
	s_lshl_b32 s2, s5, 13
	v_and_b32_e32 v155, 32, v155
	v_bitop3_b32 v156, v143, s2, v155 bitop3:0xde
	s_lshl_b32 s2, s4, 5
	s_mov_b64 s[6:7], 0x12200000
	s_and_b32 s5, s2, 0x60
	v_lshl_add_u64 v[138:139], v[140:141], 0, s[6:7]
	v_lshl_or_b32 v142, v142, 6, v154
	s_lshl_b32 s6, s5, 7
	v_bitop3_b32 v163, v142, s6, v155 bitop3:0xde
	v_and_b32_e32 v142, 48, v145
	v_mov_b32_e32 v143, v1
	v_lshrrev_b32_e32 v152, 1, v0
	s_lshl_b32 s6, s4, 1
	v_bfe_u32 v0, v0, 2, 4
	v_lshl_add_u64 v[140:141], v[140:141], 0, v[142:143]
	v_lshlrev_b32_e32 v142, 15, v146
	v_or_b32_e32 v166, s2, v0
	s_or_b32 s2, s6, 1
	v_and_b32_e32 v142, 0xffff0000, v142
	s_waitcnt vmcnt(0)
	s_lshl_b32 s4, s4, 11
	s_lshl_b32 s6, s2, 10
	v_readlane_b32 s7, v254, 11
	v_lshl_add_u32 v142, v144, 12, v142
	v_and_b32_e32 v143, 1, v146
	v_lshl_or_b32 v167, s2, 4, v0
	s_cmpk_lt_u32 s3, 0x100
	s_mov_b64 s[8:9], 0x3c800000
	v_add_u32_e32 v0, s7, v153
	v_lshl_or_b32 v142, v143, 6, v142
	s_cselect_b64 s[2:3], -1, 0
	s_ashr_i32 s24, s14, 31
	v_lshl_add_u64 v[140:141], v[140:141], 0, s[8:9]
	v_and_or_b32 v168, v152, 24, s5
	v_lshl_add_u32 v142, v147, 1, v142
	v_mov_b32_e32 v143, v1
	s_mov_b32 s25, 0
	v_add_u32_e32 v169, 0, v156
	v_add_u32_e32 v170, v0, v154
	s_add_i32 s26, s7, s4
	s_add_i32 s27, s7, s6
	s_barrier
	s_branch .LBB0_1161

.LBB0_1161:
	s_add_i32 s25, s25, 1
	s_mul_i32 s4, s25, s24
	s_mul_hi_u32 s5, s25, s14
	s_add_i32 s5, s5, s4
	s_mul_i32 s4, s25, s14
	s_add_u32 s12, s4, s15
	s_addc_u32 s13, s5, s17
	v_mov_b64_e32 v[144:145], 0x1400
	v_cmp_lt_i64_e64 s[4:5], s[12:13], v[144:145]
	v_mov_b64_e32 v[144:145], 0x13ff
	v_cmp_gt_i64_e32 vcc, s[12:13], v[144:145]
	s_cbranch_vccnz .LBB0_1163
	s_ashr_i32 s6, s12, 31
	s_lshr_b32 s6, s6, 29
	s_add_i32 s6, s12, s6
	s_ashr_i32 s7, s6, 3
	s_and_b32 s6, s6, -8
	s_sub_i32 s6, s12, s6
	s_cmp_lt_i32 s6, 0
	s_movk_i32 s8, 0x281
	s_cselect_b32 s8, s8, 0x280
	s_mul_i32 s6, s6, s8
	s_add_i32 s6, s6, s7
	s_ashr_i32 s7, s6, 31
	s_lshr_b32 s7, s7, 24
	s_add_i32 s7, s6, s7
	s_ashr_i32 s8, s7, 8
	s_lshl_b32 s8, s8, 3
	s_and_b32 s7, s7, 0xffffff00
	s_sub_i32 s7, s6, s7
	s_lshr_b32 s6, s7, 3
	s_and_b32 s7, s7, 7
	s_add_i32 s8, s8, s7
.LBB0_1163:
	s_ashr_i32 s9, s8, 31
	s_lshl_b64 s[12:13], s[8:9], 20
	s_ashr_i32 s7, s6, 31
	v_lshl_add_u64 v[144:145], v[132:133], 0, s[12:13]
	s_lshl_b64 s[12:13], s[6:7], 20
	s_lshl_b32 s7, s10, 8
	v_add_u32_e32 v156, s7, v166
	v_ashrrev_i32_e32 v157, 31, v156
	v_lshlrev_b64 v[158:159], 6, v[156:157]
	v_add_u32_e32 v156, s7, v167
	v_ashrrev_i32_e32 v157, 31, v156
	v_lshl_add_u64 v[146:147], v[130:131], 0, s[12:13]
	v_lshlrev_b64 v[156:157], 6, v[156:157]
	v_cndmask_b32_e64 v153, v151, v145, s[4:5]
	v_cndmask_b32_e64 v0, v150, v144, s[4:5]
	v_cndmask_b32_e64 v155, v149, v147, s[4:5]
	v_cndmask_b32_e64 v152, v148, v146, s[4:5]
	v_lshl_add_u64 v[156:157], v[140:141], 0, v[156:157]
	v_lshl_add_u64 v[158:159], v[140:141], 0, v[158:159]
	v_lshl_add_u64 v[150:151], v[150:151], 0, s[66:67]
	v_lshl_add_u64 v[148:149], v[148:149], 0, s[72:73]
	s_mov_b32 s9, -2
	s_mov_b64 vcc, 0
	s_add_i32 s10, 0, 0x10000
	v_add_u32_e32 v154, s10, v163
	s_add_i32 s12, 0, 0x14000
	ds_read_b128 v[172:175], v154
	ds_read_b128 v[176:179], v154 offset:1024
	ds_read_b128 v[180:183], v154 offset:2048
	ds_read_b128 v[184:187], v154 offset:3072
	v_add_u32_e32 v154, s12, v163
	ds_read_b128 v[188:191], v154
	ds_read_b128 v[192:195], v154 offset:1024
	ds_read_b128 v[196:199], v154 offset:2048
	ds_read_b128 v[200:203], v154 offset:3072
	v_lshl_add_u64 v[164:165], v[150:151], 0, s[74:75]
	v_cndmask_b32_e32 v165, v165, v153, vcc
	v_cndmask_b32_e32 v164, v164, v0, vcc
	v_cndmask_b32_e32 v205, v149, v155, vcc
	v_cndmask_b32_e32 v204, v148, v152, vcc
	v_lshl_add_u64 v[206:207], v[150:151], 0, v[142:143]
	s_add_i32 m0, s18, 0xc000
	ds_read_b128 v[210:213], v169
	ds_read_b128 v[214:217], v169 offset:1024
	ds_read_b128 v[218:221], v169 offset:2048
	ds_read_b128 v[222:225], v169 offset:3072
	ds_read_b128 v[226:229], v169 offset:4096
	ds_read_b128 v[230:233], v169 offset:5120
	ds_read_b128 v[234:237], v169 offset:6144
	ds_read_b128 v[250:253], v169 offset:7168
	global_load_lds_dwordx4 v[206:207], off
	v_lshl_add_u64 v[206:207], v[206:207], 0, s[52:53]
	s_add_i32 m0, s18, 0xe000
	s_nop 0
	global_load_lds_dwordx4 v[206:207], off
	s_waitcnt vmcnt(24)
	s_waitcnt lgkmcnt(0)
	s_barrier
	s_setprio 1
	s_waitcnt lgkmcnt(0)
	v_mfma_f32_16x16x32_bf16 v[126:129], v[172:175], v[210:213], 0
	v_mfma_f32_16x16x32_bf16 v[122:125], v[180:183], v[210:213], 0
	v_mfma_f32_16x16x32_bf16 v[110:113], v[172:175], v[218:221], 0
	v_mfma_f32_16x16x32_bf16 v[106:109], v[180:183], v[218:221], 0
	v_mfma_f32_16x16x32_bf16 v[94:97], v[172:175], v[226:229], 0
	v_mfma_f32_16x16x32_bf16 v[90:93], v[180:183], v[226:229], 0
	v_mfma_f32_16x16x32_bf16 v[78:81], v[172:175], v[234:237], 0
	v_mfma_f32_16x16x32_bf16 v[74:77], v[180:183], v[234:237], 0
	v_mfma_f32_16x16x32_bf16 v[126:129], v[176:179], v[214:217], v[126:129]
	v_mfma_f32_16x16x32_bf16 v[122:125], v[184:187], v[214:217], v[122:125]
	v_mfma_f32_16x16x32_bf16 v[110:113], v[176:179], v[222:225], v[110:113]
	v_mfma_f32_16x16x32_bf16 v[106:109], v[184:187], v[222:225], v[106:109]
	v_mfma_f32_16x16x32_bf16 v[94:97], v[176:179], v[230:233], v[94:97]
	v_mfma_f32_16x16x32_bf16 v[90:93], v[184:187], v[230:233], v[90:93]
	v_mfma_f32_16x16x32_bf16 v[78:81], v[176:179], v[250:253], v[78:81]
	v_mfma_f32_16x16x32_bf16 v[74:77], v[184:187], v[250:253], v[74:77]
	s_setprio 0
	s_setprio 1
	v_mfma_f32_16x16x32_bf16 v[118:121], v[188:191], v[210:213], 0
	v_mfma_f32_16x16x32_bf16 v[114:117], v[196:199], v[210:213], 0
	v_mfma_f32_16x16x32_bf16 v[102:105], v[188:191], v[218:221], 0
	v_mfma_f32_16x16x32_bf16 v[98:101], v[196:199], v[218:221], 0
	v_mfma_f32_16x16x32_bf16 v[86:89], v[188:191], v[226:229], 0
	v_mfma_f32_16x16x32_bf16 v[82:85], v[196:199], v[226:229], 0
	v_mfma_f32_16x16x32_bf16 v[70:73], v[188:191], v[234:237], 0
	v_mfma_f32_16x16x32_bf16 v[66:69], v[196:199], v[234:237], 0
	v_mfma_f32_16x16x32_bf16 v[118:121], v[192:195], v[214:217], v[118:121]
	v_mfma_f32_16x16x32_bf16 v[114:117], v[200:203], v[214:217], v[114:117]
	v_mfma_f32_16x16x32_bf16 v[102:105], v[192:195], v[222:225], v[102:105]
	v_mfma_f32_16x16x32_bf16 v[98:101], v[200:203], v[222:225], v[98:101]
	v_mfma_f32_16x16x32_bf16 v[86:89], v[192:195], v[230:233], v[86:89]
	v_mfma_f32_16x16x32_bf16 v[82:85], v[200:203], v[230:233], v[82:85]
	v_mfma_f32_16x16x32_bf16 v[70:73], v[192:195], v[250:253], v[70:73]
	v_mfma_f32_16x16x32_bf16 v[66:69], v[200:203], v[250:253], v[66:69]
	s_setprio 0
	s_barrier
	s_add_i32 s10, s10, s16
	v_lshl_add_u64 v[204:205], v[204:205], 0, v[134:135]
	s_mov_b32 m0, s10
	ds_read_b128 v[210:213], v169 offset:16384
	ds_read_b128 v[214:217], v169 offset:17408
	ds_read_b128 v[218:221], v169 offset:18432
	ds_read_b128 v[222:225], v169 offset:19456
	ds_read_b128 v[226:229], v169 offset:20480
	ds_read_b128 v[230:233], v169 offset:21504
	ds_read_b128 v[234:237], v169 offset:22528
	ds_read_b128 v[250:253], v169 offset:23552
	global_load_lds_dwordx4 v[204:205], off
	v_lshl_add_u64 v[206:207], v[204:205], 0, s[52:53]
	s_add_i32 m0, s10, 0x2000
	s_add_i32 s10, s12, s16
	global_load_lds_dwordx4 v[206:207], off
	v_lshl_add_u64 v[206:207], v[204:205], 0, s[54:55]
	s_mov_b32 m0, s10
	v_lshl_add_u64 v[164:165], v[164:165], 0, v[136:137]
	global_load_lds_dwordx4 v[206:207], off
	v_lshl_add_u64 v[206:207], v[204:205], 0, s[56:57]
	s_add_i32 m0, s10, 0x2000
	s_nop 0
	global_load_lds_dwordx4 v[206:207], off
	s_mov_b32 m0, s18
	v_lshl_add_u64 v[206:207], v[164:165], 0, s[52:53]
	global_load_lds_dwordx4 v[164:165], off
	s_mov_b32 m0, s19
	s_nop 0
	global_load_lds_dwordx4 v[206:207], off
	s_waitcnt vmcnt(24)
	s_waitcnt lgkmcnt(0)
	s_barrier
	s_setprio 1
	s_waitcnt lgkmcnt(0)
	v_mfma_f32_16x16x32_bf16 v[62:65], v[172:175], v[210:213], 0
	v_mfma_f32_16x16x32_bf16 v[58:61], v[180:183], v[210:213], 0
	v_mfma_f32_16x16x32_bf16 v[46:49], v[172:175], v[218:221], 0
	v_mfma_f32_16x16x32_bf16 v[42:45], v[180:183], v[218:221], 0
	v_mfma_f32_16x16x32_bf16 v[30:33], v[172:175], v[226:229], 0
	v_mfma_f32_16x16x32_bf16 v[26:29], v[180:183], v[226:229], 0
	v_mfma_f32_16x16x32_bf16 v[14:17], v[172:175], v[234:237], 0
	v_mfma_f32_16x16x32_bf16 v[10:13], v[180:183], v[234:237], 0
	v_mfma_f32_16x16x32_bf16 v[62:65], v[176:179], v[214:217], v[62:65]
	v_mfma_f32_16x16x32_bf16 v[58:61], v[184:187], v[214:217], v[58:61]
	v_mfma_f32_16x16x32_bf16 v[46:49], v[176:179], v[222:225], v[46:49]
	v_mfma_f32_16x16x32_bf16 v[42:45], v[184:187], v[222:225], v[42:45]
	v_mfma_f32_16x16x32_bf16 v[30:33], v[176:179], v[230:233], v[30:33]
	v_mfma_f32_16x16x32_bf16 v[26:29], v[184:187], v[230:233], v[26:29]
	v_mfma_f32_16x16x32_bf16 v[14:17], v[176:179], v[250:253], v[14:17]
	v_mfma_f32_16x16x32_bf16 v[10:13], v[184:187], v[250:253], v[10:13]
	s_setprio 0
	s_setprio 1
	v_mfma_f32_16x16x32_bf16 v[54:57], v[188:191], v[210:213], 0
	v_mfma_f32_16x16x32_bf16 v[50:53], v[196:199], v[210:213], 0
	v_mfma_f32_16x16x32_bf16 v[38:41], v[188:191], v[218:221], 0
	v_mfma_f32_16x16x32_bf16 v[34:37], v[196:199], v[218:221], 0
	v_mfma_f32_16x16x32_bf16 v[22:25], v[188:191], v[226:229], 0
	v_mfma_f32_16x16x32_bf16 v[18:21], v[196:199], v[226:229], 0
	v_mfma_f32_16x16x32_bf16 v[2:5], v[188:191], v[234:237], 0
	v_mfma_f32_16x16x32_bf16 v[6:9], v[196:199], v[234:237], 0
	v_mfma_f32_16x16x32_bf16 v[54:57], v[192:195], v[214:217], v[54:57]
	v_mfma_f32_16x16x32_bf16 v[50:53], v[200:203], v[214:217], v[50:53]
	v_mfma_f32_16x16x32_bf16 v[38:41], v[192:195], v[222:225], v[38:41]
	v_mfma_f32_16x16x32_bf16 v[34:37], v[200:203], v[222:225], v[34:37]
	v_mfma_f32_16x16x32_bf16 v[22:25], v[192:195], v[230:233], v[22:25]
	v_mfma_f32_16x16x32_bf16 v[18:21], v[200:203], v[230:233], v[18:21]
	v_mfma_f32_16x16x32_bf16 v[2:5], v[192:195], v[250:253], v[2:5]
	v_mfma_f32_16x16x32_bf16 v[6:9], v[200:203], v[250:253], v[6:9]
	s_setprio 0
	s_barrier
	s_add_i32 s10, 0, 0x18000
	v_add_u32_e32 v154, s10, v163
	s_add_i32 s12, 0, 0x1c000
	ds_read_b128 v[172:175], v154
	ds_read_b128 v[176:179], v154 offset:1024
	ds_read_b128 v[180:183], v154 offset:2048
	ds_read_b128 v[184:187], v154 offset:3072
	v_add_u32_e32 v154, s12, v163
	ds_read_b128 v[188:191], v154
	ds_read_b128 v[192:195], v154 offset:1024
	ds_read_b128 v[196:199], v154 offset:2048
	ds_read_b128 v[200:203], v154 offset:3072
	s_mov_b32 m0, s20
	v_lshl_add_u64 v[206:207], v[164:165], 0, s[54:55]
	ds_read_b128 v[210:213], v169 offset:32768
	ds_read_b128 v[214:217], v169 offset:33792
	ds_read_b128 v[218:221], v169 offset:34816
	ds_read_b128 v[222:225], v169 offset:35840
	ds_read_b128 v[226:229], v169 offset:36864
	ds_read_b128 v[230:233], v169 offset:37888
	ds_read_b128 v[234:237], v169 offset:38912
	ds_read_b128 v[250:253], v169 offset:39936
	global_load_lds_dwordx4 v[206:207], off
	v_lshl_add_u64 v[206:207], v[164:165], 0, s[56:57]
	s_mov_b32 m0, s21
	s_nop 0
	global_load_lds_dwordx4 v[206:207], off
	s_waitcnt vmcnt(8)
	s_waitcnt lgkmcnt(0)
	s_barrier
	s_setprio 1
	s_waitcnt lgkmcnt(0)
	v_mfma_f32_16x16x32_bf16 v[126:129], v[172:175], v[210:213], v[126:129]
	v_mfma_f32_16x16x32_bf16 v[122:125], v[180:183], v[210:213], v[122:125]
	v_mfma_f32_16x16x32_bf16 v[110:113], v[172:175], v[218:221], v[110:113]
	v_mfma_f32_16x16x32_bf16 v[106:109], v[180:183], v[218:221], v[106:109]
	v_mfma_f32_16x16x32_bf16 v[94:97], v[172:175], v[226:229], v[94:97]
	v_mfma_f32_16x16x32_bf16 v[90:93], v[180:183], v[226:229], v[90:93]
	v_mfma_f32_16x16x32_bf16 v[78:81], v[172:175], v[234:237], v[78:81]
	v_mfma_f32_16x16x32_bf16 v[74:77], v[180:183], v[234:237], v[74:77]
	v_mfma_f32_16x16x32_bf16 v[126:129], v[176:179], v[214:217], v[126:129]
	v_mfma_f32_16x16x32_bf16 v[122:125], v[184:187], v[214:217], v[122:125]
	v_mfma_f32_16x16x32_bf16 v[110:113], v[176:179], v[222:225], v[110:113]
	v_mfma_f32_16x16x32_bf16 v[106:109], v[184:187], v[222:225], v[106:109]
	v_mfma_f32_16x16x32_bf16 v[94:97], v[176:179], v[230:233], v[94:97]
	v_mfma_f32_16x16x32_bf16 v[90:93], v[184:187], v[230:233], v[90:93]
	v_mfma_f32_16x16x32_bf16 v[78:81], v[176:179], v[250:253], v[78:81]
	v_mfma_f32_16x16x32_bf16 v[74:77], v[184:187], v[250:253], v[74:77]
	s_setprio 0
	s_setprio 1
	v_mfma_f32_16x16x32_bf16 v[118:121], v[188:191], v[210:213], v[118:121]
	v_mfma_f32_16x16x32_bf16 v[114:117], v[196:199], v[210:213], v[114:117]
	v_mfma_f32_16x16x32_bf16 v[102:105], v[188:191], v[218:221], v[102:105]
	v_mfma_f32_16x16x32_bf16 v[98:101], v[196:199], v[218:221], v[98:101]
	v_mfma_f32_16x16x32_bf16 v[86:89], v[188:191], v[226:229], v[86:89]
	v_mfma_f32_16x16x32_bf16 v[82:85], v[196:199], v[226:229], v[82:85]
	v_mfma_f32_16x16x32_bf16 v[70:73], v[188:191], v[234:237], v[70:73]
	v_mfma_f32_16x16x32_bf16 v[66:69], v[196:199], v[234:237], v[66:69]
	v_mfma_f32_16x16x32_bf16 v[118:121], v[192:195], v[214:217], v[118:121]
	v_mfma_f32_16x16x32_bf16 v[114:117], v[200:203], v[214:217], v[114:117]
	v_mfma_f32_16x16x32_bf16 v[102:105], v[192:195], v[222:225], v[102:105]
	v_mfma_f32_16x16x32_bf16 v[98:101], v[200:203], v[222:225], v[98:101]
	v_mfma_f32_16x16x32_bf16 v[86:89], v[192:195], v[230:233], v[86:89]
	v_mfma_f32_16x16x32_bf16 v[82:85], v[200:203], v[230:233], v[82:85]
	v_mfma_f32_16x16x32_bf16 v[70:73], v[192:195], v[250:253], v[70:73]
	v_mfma_f32_16x16x32_bf16 v[66:69], v[200:203], v[250:253], v[66:69]
	s_setprio 0
	s_barrier
	s_add_i32 s10, s10, s16
	v_lshl_add_u64 v[206:207], v[204:205], 0, s[62:63]
	s_mov_b32 m0, s10
	ds_read_b128 v[210:213], v169 offset:49152
	ds_read_b128 v[214:217], v169 offset:50176
	ds_read_b128 v[218:221], v169 offset:51200
	ds_read_b128 v[222:225], v169 offset:52224
	ds_read_b128 v[226:229], v169 offset:53248
	ds_read_b128 v[230:233], v169 offset:54272
	ds_read_b128 v[234:237], v169 offset:55296
	ds_read_b128 v[250:253], v169 offset:56320
	global_load_lds_dwordx4 v[206:207], off
	v_lshl_add_u64 v[206:207], v[204:205], 0, s[64:65]
	s_add_i32 m0, s10, 0x2000
	s_add_i32 s10, s12, s16
	global_load_lds_dwordx4 v[206:207], off
	v_lshl_add_u64 v[206:207], v[204:205], 0, s[66:67]
	s_mov_b32 m0, s10
	v_lshl_add_u64 v[204:205], v[204:205], 0, s[68:69]
	global_load_lds_dwordx4 v[206:207], off
	s_add_i32 m0, s10, 0x2000
	s_nop 0
	global_load_lds_dwordx4 v[204:205], off
	v_lshl_add_u64 v[204:205], v[164:165], 0, s[62:63]
	s_mov_b32 m0, s22
	v_lshl_add_u64 v[164:165], v[164:165], 0, s[64:65]
	global_load_lds_dwordx4 v[204:205], off
	s_mov_b32 m0, s23
	s_nop 0
	global_load_lds_dwordx4 v[164:165], off
	s_waitcnt vmcnt(8)
	s_waitcnt lgkmcnt(0)
	s_barrier
	s_setprio 1
	s_waitcnt lgkmcnt(0)
	v_mfma_f32_16x16x32_bf16 v[62:65], v[172:175], v[210:213], v[62:65]
	v_mfma_f32_16x16x32_bf16 v[58:61], v[180:183], v[210:213], v[58:61]
	v_mfma_f32_16x16x32_bf16 v[46:49], v[172:175], v[218:221], v[46:49]
	v_mfma_f32_16x16x32_bf16 v[42:45], v[180:183], v[218:221], v[42:45]
	v_mfma_f32_16x16x32_bf16 v[30:33], v[172:175], v[226:229], v[30:33]
	v_mfma_f32_16x16x32_bf16 v[26:29], v[180:183], v[226:229], v[26:29]
	v_mfma_f32_16x16x32_bf16 v[14:17], v[172:175], v[234:237], v[14:17]
	v_mfma_f32_16x16x32_bf16 v[10:13], v[180:183], v[234:237], v[10:13]
	v_mfma_f32_16x16x32_bf16 v[62:65], v[176:179], v[214:217], v[62:65]
	v_mfma_f32_16x16x32_bf16 v[58:61], v[184:187], v[214:217], v[58:61]
	v_mfma_f32_16x16x32_bf16 v[46:49], v[176:179], v[222:225], v[46:49]
	v_mfma_f32_16x16x32_bf16 v[42:45], v[184:187], v[222:225], v[42:45]
	v_mfma_f32_16x16x32_bf16 v[30:33], v[176:179], v[230:233], v[30:33]
	v_mfma_f32_16x16x32_bf16 v[26:29], v[184:187], v[230:233], v[26:29]
	v_mfma_f32_16x16x32_bf16 v[14:17], v[176:179], v[250:253], v[14:17]
	v_mfma_f32_16x16x32_bf16 v[10:13], v[184:187], v[250:253], v[10:13]
	s_setprio 0
	s_setprio 1
	v_mfma_f32_16x16x32_bf16 v[54:57], v[188:191], v[210:213], v[54:57]
	v_mfma_f32_16x16x32_bf16 v[50:53], v[196:199], v[210:213], v[50:53]
	v_mfma_f32_16x16x32_bf16 v[38:41], v[188:191], v[218:221], v[38:41]
	v_mfma_f32_16x16x32_bf16 v[34:37], v[196:199], v[218:221], v[34:37]
	v_mfma_f32_16x16x32_bf16 v[22:25], v[188:191], v[226:229], v[22:25]
	v_mfma_f32_16x16x32_bf16 v[18:21], v[196:199], v[226:229], v[18:21]
	v_mfma_f32_16x16x32_bf16 v[2:5], v[188:191], v[234:237], v[2:5]
	v_mfma_f32_16x16x32_bf16 v[6:9], v[196:199], v[234:237], v[6:9]
	v_mfma_f32_16x16x32_bf16 v[54:57], v[192:195], v[214:217], v[54:57]
	v_mfma_f32_16x16x32_bf16 v[50:53], v[200:203], v[214:217], v[50:53]
	v_mfma_f32_16x16x32_bf16 v[38:41], v[192:195], v[222:225], v[38:41]
	v_mfma_f32_16x16x32_bf16 v[34:37], v[200:203], v[222:225], v[34:37]
	v_mfma_f32_16x16x32_bf16 v[22:25], v[192:195], v[230:233], v[22:25]
	v_mfma_f32_16x16x32_bf16 v[18:21], v[200:203], v[230:233], v[18:21]
	v_mfma_f32_16x16x32_bf16 v[2:5], v[192:195], v[250:253], v[2:5]
	v_mfma_f32_16x16x32_bf16 v[6:9], v[200:203], v[250:253], v[6:9]
	s_setprio 0
	s_barrier
	s_add_i32 s9, s9, 2
	v_lshl_add_u64 v[150:151], v[150:151], 0, s[72:73]
	s_cmp_gt_u32 s9, 29
	v_lshl_add_u64 v[148:149], v[148:149], 0, s[72:73]
	s_branch .LBB0_1165

.LBB0_1228:
	v_lshl_add_u64 v[146:147], v[136:137], 0, s[62:63]
	s_add_i32 m0, s21, 0x18000
	s_waitcnt vmcnt(2)
	s_barrier
	global_load_lds_dwordx4 v[146:147], off
	v_lshl_add_u64 v[146:147], v[136:137], 0, s[70:71]
	s_add_i32 m0, s21, 0x1a000
	s_add_i32 s25, s21, 0x8000
	global_load_lds_dwordx4 v[146:147], off
	v_lshl_add_u64 v[146:147], v[138:139], 0, s[62:63]
	s_mov_b32 m0, s25
	s_add_i32 s26, s21, 0xa000
	global_load_lds_dwordx4 v[146:147], off
	v_lshl_add_u64 v[138:139], v[138:139], 0, s[70:71]
	s_mov_b32 m0, s26
	s_and_b32 s27, s3, 3
	global_load_lds_dwordx4 v[138:139], off
	v_lshl_add_u64 v[138:139], v[136:137], 0, s[96:97]
	s_add_i32 m0, s21, 0x1c000
	v_lshl_add_u64 v[136:137], v[136:137], 0, s[88:89]
	global_load_lds_dwordx4 v[138:139], off
	s_add_i32 m0, s21, 0x1e000
	s_lshl_b32 s3, s4, 13
	global_load_lds_dwordx4 v[136:137], off
	v_bfe_u32 v137, v0, 4, 2
	v_and_b32_e32 v136, 15, v0
	v_lshlrev_b32_e32 v139, 4, v137
	v_lshlrev_b32_e32 v0, 2, v0
	v_lshl_or_b32 v250, s4, 6, v136
	v_lshl_or_b32 v136, v136, 6, v139
	v_and_b32_e32 v0, 32, v0
	v_bitop3_b32 v139, v136, s3, v0 bitop3:0xde
	s_lshl_b32 s3, s27, 12
	v_bitop3_b32 v251, v136, s3, v0 bitop3:0xde
	v_lshlrev_b32_e32 v0, 17, v142
	v_and_b32_e32 v0, 0xfffc0000, v0
	s_waitcnt vmcnt(0)
	v_lshl_add_u32 v0, v143, 14, v0
	v_and_b32_e32 v136, 1, v142
	v_lshlrev_b32_e32 v138, 3, v137
	s_mov_b64 s[4:5], 0x3c200000
	s_cmpk_lt_u32 s2, 0x100
	v_lshl_or_b32 v0, v136, 6, v0
	v_lshl_add_u64 v[4:5], v[4:5], 0, s[4:5]
	v_lshl_or_b32 v252, s27, 5, v138
	s_cselect_b64 s[2:3], -1, 0
	s_mov_b32 s28, 0
	v_cmp_eq_u32_e64 s[4:5], 0, v137
	s_ashr_i32 s29, s18, 31
	s_ashr_i32 s30, s19, 31
	v_lshl_add_u32 v212, v144, 1, v0
	v_mov_b32_e32 v213, v1
	v_add_u32_e32 v253, 0, v139
	s_barrier
	s_branch .LBB0_1231

.LBB0_1231:
	s_add_i32 s28, s28, 1
	s_mul_i32 s6, s28, s29
	s_mul_hi_u32 s7, s28, s18
	s_add_i32 s7, s7, s6
	s_mul_i32 s6, s28, s18
	s_add_u32 s16, s6, s19
	s_addc_u32 s17, s7, s30
	v_mov_b64_e32 v[136:137], 0x4ff
	v_cmp_gt_i64_e32 vcc, s[16:17], v[136:137]
	v_cmp_lt_i64_e64 s[6:7], s[16:17], v[242:243]
	s_cbranch_vccnz .LBB0_1233
	s_ashr_i32 s8, s16, 31
	s_lshr_b32 s8, s8, 29
	s_add_i32 s8, s16, s8
	s_ashr_i32 s9, s8, 3
	s_and_b32 s8, s8, -8
	s_sub_i32 s8, s16, s8
	s_cmp_lt_i32 s8, 0
	s_movk_i32 s10, 0xa1
	s_cselect_b32 s10, s10, 0xa0
	s_mul_i32 s8, s8, s10
	s_add_i32 s8, s8, s9
	s_ashr_i32 s9, s8, 31
	s_lshr_b32 s9, s9, 26
	s_add_i32 s9, s8, s9
	s_ashr_i32 s10, s9, 5
	s_lshl_b32 s10, s10, 2
	s_andn2_b32 s9, s9, 31
	s_sub_i32 s9, s8, s9
	s_lshr_b32 s8, s9, 2
	s_and_b32 s9, s9, 3
	s_add_i32 s10, s10, s9
.LBB0_1233:
	s_ashr_i32 s11, s10, 31
	s_lshl_b64 s[16:17], s[10:11], 22
	s_ashr_i32 s9, s8, 31
	v_lshl_add_u64 v[214:215], v[202:203], 0, s[16:17]
	s_lshl_b64 s[16:17], s[8:9], 22
	v_lshl_add_u64 v[216:217], v[198:199], 0, s[16:17]
	v_cndmask_b32_e64 v137, v141, v215, s[6:7]
	v_cndmask_b32_e64 v0, v140, v214, s[6:7]
	v_cndmask_b32_e64 v139, v135, v217, s[6:7]
	v_cndmask_b32_e64 v136, v134, v216, s[6:7]
	v_lshl_add_u64 v[140:141], v[140:141], 0, s[96:97]
	v_lshl_add_u64 v[134:135], v[134:135], 0, s[72:73]
	s_mov_b32 s9, -2
	s_cmpk_eq_i32 s9, 0x7c
	s_cselect_b64 vcc, -1, 0
	s_add_i32 s11, 0, 0x10000
	v_lshl_add_u64 v[142:143], v[140:141], 0, s[48:49]
	v_add_u32_e32 v138, s11, v251
	s_add_i32 s13, 0, 0x14000
	v_cndmask_b32_e32 v207, v143, v137, vcc
	v_cndmask_b32_e32 v206, v142, v0, vcc
	ds_read_b128 v[142:145], v138
	ds_read_b128 v[146:149], v138 offset:1024
	ds_read_b128 v[150:153], v138 offset:2048
	ds_read_b128 v[154:157], v138 offset:3072
	v_add_u32_e32 v138, s13, v251
	ds_read_b128 v[158:161], v138
	ds_read_b128 v[162:165], v138 offset:1024
	ds_read_b128 v[166:169], v138 offset:2048
	ds_read_b128 v[170:173], v138 offset:3072
	v_cndmask_b32_e32 v227, v135, v139, vcc
	v_cndmask_b32_e32 v226, v134, v136, vcc
	v_lshl_add_u64 v[228:229], v[140:141], 0, v[212:213]
	s_add_i32 m0, s21, 0xc000
	ds_read_b128 v[174:177], v253
	ds_read_b128 v[178:181], v253 offset:1024
	ds_read_b128 v[182:185], v253 offset:2048
	ds_read_b128 v[186:189], v253 offset:3072
	ds_read_b128 v[190:193], v253 offset:4096
	ds_read_b128 v[194:197], v253 offset:5120
	ds_read_b128 v[218:221], v253 offset:6144
	ds_read_b128 v[222:225], v253 offset:7168
	global_load_lds_dwordx4 v[228:229], off
	v_lshl_add_u64 v[228:229], v[228:229], 0, s[84:85]
	s_add_i32 m0, s21, 0xe000
	s_nop 0
	global_load_lds_dwordx4 v[228:229], off
	s_waitcnt vmcnt(24)
	s_waitcnt lgkmcnt(0)
	s_barrier
	s_setprio 1
	s_waitcnt lgkmcnt(0)
	v_mfma_f32_16x16x32_bf16 v[126:129], v[142:145], v[174:177], 0
	v_mfma_f32_16x16x32_bf16 v[130:133], v[150:153], v[174:177], 0
	v_mfma_f32_16x16x32_bf16 v[114:117], v[142:145], v[182:185], 0
	v_mfma_f32_16x16x32_bf16 v[110:113], v[150:153], v[182:185], 0
	v_mfma_f32_16x16x32_bf16 v[98:101], v[142:145], v[190:193], 0
	v_mfma_f32_16x16x32_bf16 v[94:97], v[150:153], v[190:193], 0
	v_mfma_f32_16x16x32_bf16 v[82:85], v[142:145], v[218:221], 0
	v_mfma_f32_16x16x32_bf16 v[78:81], v[150:153], v[218:221], 0
	v_mfma_f32_16x16x32_bf16 v[126:129], v[146:149], v[178:181], v[126:129]
	v_mfma_f32_16x16x32_bf16 v[130:133], v[154:157], v[178:181], v[130:133]
	v_mfma_f32_16x16x32_bf16 v[114:117], v[146:149], v[186:189], v[114:117]
	v_mfma_f32_16x16x32_bf16 v[110:113], v[154:157], v[186:189], v[110:113]
	v_mfma_f32_16x16x32_bf16 v[98:101], v[146:149], v[194:197], v[98:101]
	v_mfma_f32_16x16x32_bf16 v[94:97], v[154:157], v[194:197], v[94:97]
	v_mfma_f32_16x16x32_bf16 v[82:85], v[146:149], v[222:225], v[82:85]
	v_mfma_f32_16x16x32_bf16 v[78:81], v[154:157], v[222:225], v[78:81]
	s_setprio 0
	s_setprio 1
	v_mfma_f32_16x16x32_bf16 v[122:125], v[158:161], v[174:177], 0
	v_mfma_f32_16x16x32_bf16 v[118:121], v[166:169], v[174:177], 0
	v_mfma_f32_16x16x32_bf16 v[106:109], v[158:161], v[182:185], 0
	v_mfma_f32_16x16x32_bf16 v[102:105], v[166:169], v[182:185], 0
	v_mfma_f32_16x16x32_bf16 v[90:93], v[158:161], v[190:193], 0
	v_mfma_f32_16x16x32_bf16 v[86:89], v[166:169], v[190:193], 0
	v_mfma_f32_16x16x32_bf16 v[74:77], v[158:161], v[218:221], 0
	v_mfma_f32_16x16x32_bf16 v[70:73], v[166:169], v[218:221], 0
	v_mfma_f32_16x16x32_bf16 v[122:125], v[162:165], v[178:181], v[122:125]
	v_mfma_f32_16x16x32_bf16 v[118:121], v[170:173], v[178:181], v[118:121]
	v_mfma_f32_16x16x32_bf16 v[106:109], v[162:165], v[186:189], v[106:109]
	v_mfma_f32_16x16x32_bf16 v[102:105], v[170:173], v[186:189], v[102:105]
	v_mfma_f32_16x16x32_bf16 v[90:93], v[162:165], v[194:197], v[90:93]
	v_mfma_f32_16x16x32_bf16 v[86:89], v[170:173], v[194:197], v[86:89]
	v_mfma_f32_16x16x32_bf16 v[74:77], v[162:165], v[222:225], v[74:77]
	v_mfma_f32_16x16x32_bf16 v[70:73], v[170:173], v[222:225], v[70:73]
	s_setprio 0
	s_barrier
	s_add_i32 s11, s11, s20
	v_lshl_add_u64 v[226:227], v[226:227], 0, v[210:211]
	s_mov_b32 m0, s11
	ds_read_b128 v[174:177], v253 offset:16384
	ds_read_b128 v[178:181], v253 offset:17408
	ds_read_b128 v[182:185], v253 offset:18432
	ds_read_b128 v[186:189], v253 offset:19456
	ds_read_b128 v[190:193], v253 offset:20480
	ds_read_b128 v[194:197], v253 offset:21504
	ds_read_b128 v[218:221], v253 offset:22528
	ds_read_b128 v[222:225], v253 offset:23552
	global_load_lds_dwordx4 v[226:227], off
	v_lshl_add_u64 v[228:229], v[226:227], 0, s[84:85]
	s_add_i32 m0, s11, 0x2000
	s_add_i32 s11, s13, s20
	global_load_lds_dwordx4 v[228:229], off
	v_lshl_add_u64 v[228:229], v[226:227], 0, s[50:51]
	s_mov_b32 m0, s11
	v_lshl_add_u64 v[206:207], v[206:207], 0, v[204:205]
	global_load_lds_dwordx4 v[228:229], off
	v_lshl_add_u64 v[228:229], v[226:227], 0, s[94:95]
	s_add_i32 m0, s11, 0x2000
	s_nop 0
	global_load_lds_dwordx4 v[228:229], off
	s_mov_b32 m0, s21
	v_lshl_add_u64 v[228:229], v[206:207], 0, s[84:85]
	global_load_lds_dwordx4 v[206:207], off
	s_mov_b32 m0, s22
	s_nop 0
	global_load_lds_dwordx4 v[228:229], off
	s_waitcnt vmcnt(24)
	s_waitcnt lgkmcnt(0)
	s_barrier
	s_setprio 1
	s_waitcnt lgkmcnt(0)
	v_mfma_f32_16x16x32_bf16 v[66:69], v[142:145], v[174:177], 0
	v_mfma_f32_16x16x32_bf16 v[62:65], v[150:153], v[174:177], 0
	v_mfma_f32_16x16x32_bf16 v[50:53], v[142:145], v[182:185], 0
	v_mfma_f32_16x16x32_bf16 v[46:49], v[150:153], v[182:185], 0
	v_mfma_f32_16x16x32_bf16 v[34:37], v[142:145], v[190:193], 0
	v_mfma_f32_16x16x32_bf16 v[30:33], v[150:153], v[190:193], 0
	v_mfma_f32_16x16x32_bf16 v[18:21], v[142:145], v[218:221], 0
	v_mfma_f32_16x16x32_bf16 v[14:17], v[150:153], v[218:221], 0
	v_mfma_f32_16x16x32_bf16 v[66:69], v[146:149], v[178:181], v[66:69]
	v_mfma_f32_16x16x32_bf16 v[62:65], v[154:157], v[178:181], v[62:65]
	v_mfma_f32_16x16x32_bf16 v[50:53], v[146:149], v[186:189], v[50:53]
	v_mfma_f32_16x16x32_bf16 v[46:49], v[154:157], v[186:189], v[46:49]
	v_mfma_f32_16x16x32_bf16 v[34:37], v[146:149], v[194:197], v[34:37]
	v_mfma_f32_16x16x32_bf16 v[30:33], v[154:157], v[194:197], v[30:33]
	v_mfma_f32_16x16x32_bf16 v[18:21], v[146:149], v[222:225], v[18:21]
	v_mfma_f32_16x16x32_bf16 v[14:17], v[154:157], v[222:225], v[14:17]
	s_setprio 0
	s_setprio 1
	v_mfma_f32_16x16x32_bf16 v[58:61], v[158:161], v[174:177], 0
	v_mfma_f32_16x16x32_bf16 v[54:57], v[166:169], v[174:177], 0
	v_mfma_f32_16x16x32_bf16 v[42:45], v[158:161], v[182:185], 0
	v_mfma_f32_16x16x32_bf16 v[38:41], v[166:169], v[182:185], 0
	v_mfma_f32_16x16x32_bf16 v[26:29], v[158:161], v[190:193], 0
	v_mfma_f32_16x16x32_bf16 v[22:25], v[166:169], v[190:193], 0
	v_mfma_f32_16x16x32_bf16 v[10:13], v[158:161], v[218:221], 0
	v_mfma_f32_16x16x32_bf16 v[6:9], v[166:169], v[218:221], 0
	v_mfma_f32_16x16x32_bf16 v[58:61], v[162:165], v[178:181], v[58:61]
	v_mfma_f32_16x16x32_bf16 v[54:57], v[170:173], v[178:181], v[54:57]
	v_mfma_f32_16x16x32_bf16 v[42:45], v[162:165], v[186:189], v[42:45]
	v_mfma_f32_16x16x32_bf16 v[38:41], v[170:173], v[186:189], v[38:41]
	v_mfma_f32_16x16x32_bf16 v[26:29], v[162:165], v[194:197], v[26:29]
	v_mfma_f32_16x16x32_bf16 v[22:25], v[170:173], v[194:197], v[22:25]
	v_mfma_f32_16x16x32_bf16 v[10:13], v[162:165], v[222:225], v[10:13]
	v_mfma_f32_16x16x32_bf16 v[6:9], v[170:173], v[222:225], v[6:9]
	s_setprio 0
	s_barrier
	s_add_i32 s11, 0, 0x18000
	v_add_u32_e32 v138, s11, v251
	s_add_i32 s13, 0, 0x1c000
	ds_read_b128 v[142:145], v138
	ds_read_b128 v[146:149], v138 offset:1024
	ds_read_b128 v[150:153], v138 offset:2048
	ds_read_b128 v[154:157], v138 offset:3072
	v_add_u32_e32 v138, s13, v251
	ds_read_b128 v[158:161], v138
	ds_read_b128 v[162:165], v138 offset:1024
	ds_read_b128 v[166:169], v138 offset:2048
	ds_read_b128 v[170:173], v138 offset:3072
	s_mov_b32 m0, s23
	v_lshl_add_u64 v[228:229], v[206:207], 0, s[50:51]
	ds_read_b128 v[174:177], v253 offset:32768
	ds_read_b128 v[178:181], v253 offset:33792
	ds_read_b128 v[182:185], v253 offset:34816
	ds_read_b128 v[186:189], v253 offset:35840
	ds_read_b128 v[190:193], v253 offset:36864
	ds_read_b128 v[194:197], v253 offset:37888
	ds_read_b128 v[218:221], v253 offset:38912
	ds_read_b128 v[222:225], v253 offset:39936
	global_load_lds_dwordx4 v[228:229], off
	v_lshl_add_u64 v[228:229], v[206:207], 0, s[94:95]
	s_mov_b32 m0, s24
	s_nop 0
	global_load_lds_dwordx4 v[228:229], off
	s_waitcnt vmcnt(8)
	s_waitcnt lgkmcnt(0)
	s_barrier
	s_setprio 1
	s_waitcnt lgkmcnt(0)
	v_mfma_f32_16x16x32_bf16 v[126:129], v[142:145], v[174:177], v[126:129]
	v_mfma_f32_16x16x32_bf16 v[130:133], v[150:153], v[174:177], v[130:133]
	v_mfma_f32_16x16x32_bf16 v[114:117], v[142:145], v[182:185], v[114:117]
	v_mfma_f32_16x16x32_bf16 v[110:113], v[150:153], v[182:185], v[110:113]
	v_mfma_f32_16x16x32_bf16 v[98:101], v[142:145], v[190:193], v[98:101]
	v_mfma_f32_16x16x32_bf16 v[94:97], v[150:153], v[190:193], v[94:97]
	v_mfma_f32_16x16x32_bf16 v[82:85], v[142:145], v[218:221], v[82:85]
	v_mfma_f32_16x16x32_bf16 v[78:81], v[150:153], v[218:221], v[78:81]
	v_mfma_f32_16x16x32_bf16 v[126:129], v[146:149], v[178:181], v[126:129]
	v_mfma_f32_16x16x32_bf16 v[130:133], v[154:157], v[178:181], v[130:133]
	v_mfma_f32_16x16x32_bf16 v[114:117], v[146:149], v[186:189], v[114:117]
	v_mfma_f32_16x16x32_bf16 v[110:113], v[154:157], v[186:189], v[110:113]
	v_mfma_f32_16x16x32_bf16 v[98:101], v[146:149], v[194:197], v[98:101]
	v_mfma_f32_16x16x32_bf16 v[94:97], v[154:157], v[194:197], v[94:97]
	v_mfma_f32_16x16x32_bf16 v[82:85], v[146:149], v[222:225], v[82:85]
	v_mfma_f32_16x16x32_bf16 v[78:81], v[154:157], v[222:225], v[78:81]
	s_setprio 0
	s_setprio 1
	v_mfma_f32_16x16x32_bf16 v[122:125], v[158:161], v[174:177], v[122:125]
	v_mfma_f32_16x16x32_bf16 v[118:121], v[166:169], v[174:177], v[118:121]
	v_mfma_f32_16x16x32_bf16 v[106:109], v[158:161], v[182:185], v[106:109]
	v_mfma_f32_16x16x32_bf16 v[102:105], v[166:169], v[182:185], v[102:105]
	v_mfma_f32_16x16x32_bf16 v[90:93], v[158:161], v[190:193], v[90:93]
	v_mfma_f32_16x16x32_bf16 v[86:89], v[166:169], v[190:193], v[86:89]
	v_mfma_f32_16x16x32_bf16 v[74:77], v[158:161], v[218:221], v[74:77]
	v_mfma_f32_16x16x32_bf16 v[70:73], v[166:169], v[218:221], v[70:73]
	v_mfma_f32_16x16x32_bf16 v[122:125], v[162:165], v[178:181], v[122:125]
	v_mfma_f32_16x16x32_bf16 v[118:121], v[170:173], v[178:181], v[118:121]
	v_mfma_f32_16x16x32_bf16 v[106:109], v[162:165], v[186:189], v[106:109]
	v_mfma_f32_16x16x32_bf16 v[102:105], v[170:173], v[186:189], v[102:105]
	v_mfma_f32_16x16x32_bf16 v[90:93], v[162:165], v[194:197], v[90:93]
	v_mfma_f32_16x16x32_bf16 v[86:89], v[170:173], v[194:197], v[86:89]
	v_mfma_f32_16x16x32_bf16 v[74:77], v[162:165], v[222:225], v[74:77]
	v_mfma_f32_16x16x32_bf16 v[70:73], v[170:173], v[222:225], v[70:73]
	s_setprio 0
	s_barrier
	s_add_i32 s11, s11, s20
	v_lshl_add_u64 v[228:229], v[226:227], 0, s[62:63]
	s_mov_b32 m0, s11
	ds_read_b128 v[174:177], v253 offset:49152
	ds_read_b128 v[178:181], v253 offset:50176
	ds_read_b128 v[182:185], v253 offset:51200
	ds_read_b128 v[186:189], v253 offset:52224
	ds_read_b128 v[190:193], v253 offset:53248
	ds_read_b128 v[194:197], v253 offset:54272
	ds_read_b128 v[218:221], v253 offset:55296
	ds_read_b128 v[222:225], v253 offset:56320
	global_load_lds_dwordx4 v[228:229], off
	v_lshl_add_u64 v[228:229], v[226:227], 0, s[70:71]
	s_add_i32 m0, s11, 0x2000
	s_add_i32 s11, s13, s20
	global_load_lds_dwordx4 v[228:229], off
	v_lshl_add_u64 v[228:229], v[226:227], 0, s[96:97]
	s_mov_b32 m0, s11
	v_lshl_add_u64 v[226:227], v[226:227], 0, s[88:89]
	global_load_lds_dwordx4 v[228:229], off
	s_add_i32 m0, s11, 0x2000
	s_nop 0
	global_load_lds_dwordx4 v[226:227], off
	v_lshl_add_u64 v[226:227], v[206:207], 0, s[62:63]
	s_mov_b32 m0, s25
	v_lshl_add_u64 v[206:207], v[206:207], 0, s[70:71]
	global_load_lds_dwordx4 v[226:227], off
	s_mov_b32 m0, s26
	s_nop 0
	global_load_lds_dwordx4 v[206:207], off
	s_waitcnt vmcnt(8)
	s_waitcnt lgkmcnt(0)
	s_barrier
	s_setprio 1
	s_waitcnt lgkmcnt(0)
	v_mfma_f32_16x16x32_bf16 v[66:69], v[142:145], v[174:177], v[66:69]
	v_mfma_f32_16x16x32_bf16 v[62:65], v[150:153], v[174:177], v[62:65]
	v_mfma_f32_16x16x32_bf16 v[50:53], v[142:145], v[182:185], v[50:53]
	v_mfma_f32_16x16x32_bf16 v[46:49], v[150:153], v[182:185], v[46:49]
	v_mfma_f32_16x16x32_bf16 v[34:37], v[142:145], v[190:193], v[34:37]
	v_mfma_f32_16x16x32_bf16 v[30:33], v[150:153], v[190:193], v[30:33]
	v_mfma_f32_16x16x32_bf16 v[18:21], v[142:145], v[218:221], v[18:21]
	v_mfma_f32_16x16x32_bf16 v[14:17], v[150:153], v[218:221], v[14:17]
	v_mfma_f32_16x16x32_bf16 v[66:69], v[146:149], v[178:181], v[66:69]
	v_mfma_f32_16x16x32_bf16 v[62:65], v[154:157], v[178:181], v[62:65]
	v_mfma_f32_16x16x32_bf16 v[50:53], v[146:149], v[186:189], v[50:53]
	v_mfma_f32_16x16x32_bf16 v[46:49], v[154:157], v[186:189], v[46:49]
	v_mfma_f32_16x16x32_bf16 v[34:37], v[146:149], v[194:197], v[34:37]
	v_mfma_f32_16x16x32_bf16 v[30:33], v[154:157], v[194:197], v[30:33]
	v_mfma_f32_16x16x32_bf16 v[18:21], v[146:149], v[222:225], v[18:21]
	v_mfma_f32_16x16x32_bf16 v[14:17], v[154:157], v[222:225], v[14:17]
	s_setprio 0
	s_setprio 1
	v_mfma_f32_16x16x32_bf16 v[58:61], v[158:161], v[174:177], v[58:61]
	v_mfma_f32_16x16x32_bf16 v[54:57], v[166:169], v[174:177], v[54:57]
	v_mfma_f32_16x16x32_bf16 v[42:45], v[158:161], v[182:185], v[42:45]
	v_mfma_f32_16x16x32_bf16 v[38:41], v[166:169], v[182:185], v[38:41]
	v_mfma_f32_16x16x32_bf16 v[26:29], v[158:161], v[190:193], v[26:29]
	v_mfma_f32_16x16x32_bf16 v[22:25], v[166:169], v[190:193], v[22:25]
	v_mfma_f32_16x16x32_bf16 v[10:13], v[158:161], v[218:221], v[10:13]
	v_mfma_f32_16x16x32_bf16 v[6:9], v[166:169], v[218:221], v[6:9]
	v_mfma_f32_16x16x32_bf16 v[58:61], v[162:165], v[178:181], v[58:61]
	v_mfma_f32_16x16x32_bf16 v[54:57], v[170:173], v[178:181], v[54:57]
	v_mfma_f32_16x16x32_bf16 v[42:45], v[162:165], v[186:189], v[42:45]
	v_mfma_f32_16x16x32_bf16 v[38:41], v[170:173], v[186:189], v[38:41]
	v_mfma_f32_16x16x32_bf16 v[26:29], v[162:165], v[194:197], v[26:29]
	v_mfma_f32_16x16x32_bf16 v[22:25], v[170:173], v[194:197], v[22:25]
	v_mfma_f32_16x16x32_bf16 v[10:13], v[162:165], v[222:225], v[10:13]
	v_mfma_f32_16x16x32_bf16 v[6:9], v[170:173], v[222:225], v[6:9]
	s_setprio 0
	s_barrier
	s_add_i32 s9, s9, 2
	v_lshl_add_u64 v[140:141], v[140:141], 0, s[72:73]
	s_cmpk_gt_u32 s9, 0x7d
	v_lshl_add_u64 v[134:135], v[134:135], 0, s[72:73]

.LBB0_1262:
	v_lshl_add_u64 v[144:145], v[134:135], 0, s[62:63]
	s_add_i32 m0, s16, 0x18000
	s_waitcnt vmcnt(2)
	s_barrier
	global_load_lds_dwordx4 v[144:145], off
	v_lshl_add_u64 v[144:145], v[134:135], 0, s[70:71]
	s_add_i32 m0, s16, 0x1a000
	s_add_i32 s22, s16, 0x8000
	global_load_lds_dwordx4 v[144:145], off
	v_lshl_add_u64 v[144:145], v[136:137], 0, s[62:63]
	s_mov_b32 m0, s22
	s_add_i32 s23, s16, 0xa000
	global_load_lds_dwordx4 v[144:145], off
	v_lshl_add_u64 v[136:137], v[136:137], 0, s[70:71]
	s_mov_b32 m0, s23
	s_sext_i32_i8 s11, s2
	global_load_lds_dwordx4 v[136:137], off
	v_lshl_add_u64 v[136:137], v[134:135], 0, s[96:97]
	s_add_i32 m0, s16, 0x1c000
	v_lshl_add_u64 v[134:135], v[134:135], 0, s[88:89]
	global_load_lds_dwordx4 v[136:137], off
	s_add_i32 m0, s16, 0x1e000
	s_lshl_b32 s2, s5, 13
	global_load_lds_dwordx4 v[134:135], off
	v_lshrrev_b32_e32 v135, 1, v0
	v_and_b32_e32 v135, 24, v135
	v_and_b32_e32 v134, 15, v0
	v_lshlrev_b32_e32 v136, 1, v135
	v_lshlrev_b32_e32 v0, 2, v0
	v_lshl_or_b32 v230, s5, 6, v134
	v_lshl_or_b32 v134, v134, 6, v136
	v_and_b32_e32 v0, 32, v0
	v_bitop3_b32 v136, v134, s2, v0 bitop3:0xde
	s_lshl_b32 s2, s4, 5
	s_and_b32 s4, s2, 0x60
	s_lshl_b32 s2, s4, 7
	v_bitop3_b32 v231, v134, s2, v0 bitop3:0xde
	v_lshlrev_b32_e32 v0, 17, v141
	v_and_b32_e32 v0, 0xfffc0000, v0
	s_waitcnt vmcnt(0)
	v_lshl_add_u32 v0, v140, 14, v0
	v_and_b32_e32 v134, 1, v141
	s_cmpk_lt_u32 s3, 0x100
	v_lshl_or_b32 v0, v134, 6, v0
	s_cselect_b64 s[2:3], -1, 0
	s_ashr_i32 s24, s18, 31
	v_or_b32_e32 v232, s4, v135
	v_lshl_add_u32 v196, v142, 1, v0
	v_mov_b32_e32 v197, v1
	s_mov_b32 s25, 0
	v_add_u32_e32 v233, 0, v136
	s_barrier
	s_branch .LBB0_1265

.LBB0_1265:
	s_add_i32 s25, s25, 1
	s_mul_i32 s4, s25, s24
	s_mul_hi_u32 s5, s25, s18
	s_add_i32 s5, s5, s4
	s_mul_i32 s4, s25, s18
	s_add_u32 s12, s4, s19
	s_addc_u32 s13, s5, s15
	v_mov_b64_e32 v[134:135], 0x4ff
	v_cmp_gt_i64_e32 vcc, s[12:13], v[134:135]
	v_mov_b64_e32 v[252:253], 0x500
	v_cmp_lt_i64_e64 s[4:5], s[12:13], v[242:243]
	s_cbranch_vccnz .LBB0_1267
	s_ashr_i32 s6, s12, 31
	s_lshr_b32 s6, s6, 29
	s_add_i32 s6, s12, s6
	s_ashr_i32 s7, s6, 3
	s_and_b32 s6, s6, -8
	s_sub_i32 s6, s12, s6
	s_cmp_lt_i32 s6, 0
	s_movk_i32 s8, 0xa1
	s_cselect_b32 s8, s8, 0xa0
	s_mul_i32 s6, s6, s8
	s_add_i32 s6, s6, s7
	s_ashr_i32 s7, s6, 31
	s_lshr_b32 s7, s7, 26
	s_add_i32 s7, s6, s7
	s_ashr_i32 s8, s7, 5
	s_lshl_b32 s8, s8, 2
	s_andn2_b32 s7, s7, 31
	s_sub_i32 s7, s6, s7
	s_lshr_b32 s6, s7, 2
	s_and_b32 s7, s7, 3
	s_add_i32 s8, s8, s7
.LBB0_1267:
	s_ashr_i32 s9, s8, 31
	s_lshl_b64 s[12:13], s[8:9], 22
	s_ashr_i32 s7, s6, 31
	v_lshl_add_u64 v[204:205], v[202:203], 0, s[12:13]
	s_lshl_b64 s[12:13], s[6:7], 22
	v_lshl_add_u64 v[210:211], v[198:199], 0, s[12:13]
	v_cndmask_b32_e64 v135, v139, v205, s[4:5]
	v_cndmask_b32_e64 v0, v138, v204, s[4:5]
	v_cndmask_b32_e64 v137, v133, v211, s[4:5]
	v_cndmask_b32_e64 v134, v132, v210, s[4:5]
	v_lshl_add_u64 v[138:139], v[138:139], 0, s[96:97]
	v_lshl_add_u64 v[132:133], v[132:133], 0, s[72:73]
	s_mov_b32 s7, -2
	s_cmpk_eq_i32 s7, 0x7c
	s_cselect_b64 vcc, -1, 0
	s_add_i32 s9, 0, 0x10000
	v_lshl_add_u64 v[140:141], v[138:139], 0, s[48:49]
	v_add_u32_e32 v136, s9, v231
	s_add_i32 s12, 0, 0x14000
	v_cndmask_b32_e32 v207, v141, v135, vcc
	v_cndmask_b32_e32 v206, v140, v0, vcc
	ds_read_b128 v[140:143], v136
	ds_read_b128 v[144:147], v136 offset:1024
	ds_read_b128 v[148:151], v136 offset:2048
	ds_read_b128 v[152:155], v136 offset:3072
	v_add_u32_e32 v136, s12, v231
	ds_read_b128 v[156:159], v136
	ds_read_b128 v[160:163], v136 offset:1024
	ds_read_b128 v[164:167], v136 offset:2048
	ds_read_b128 v[168:171], v136 offset:3072
	v_cndmask_b32_e32 v209, v133, v137, vcc
	v_cndmask_b32_e32 v208, v132, v134, vcc
	v_lshl_add_u64 v[224:225], v[138:139], 0, v[196:197]
	s_add_i32 m0, s16, 0xc000
	ds_read_b128 v[172:175], v233
	ds_read_b128 v[176:179], v233 offset:1024
	ds_read_b128 v[180:183], v233 offset:2048
	ds_read_b128 v[184:187], v233 offset:3072
	ds_read_b128 v[188:191], v233 offset:4096
	ds_read_b128 v[212:215], v233 offset:5120
	ds_read_b128 v[216:219], v233 offset:6144
	ds_read_b128 v[220:223], v233 offset:7168
	global_load_lds_dwordx4 v[224:225], off
	v_lshl_add_u64 v[224:225], v[224:225], 0, s[84:85]
	s_add_i32 m0, s16, 0xe000
	s_nop 0
	global_load_lds_dwordx4 v[224:225], off
	s_waitcnt vmcnt(24)
	s_waitcnt lgkmcnt(0)
	s_barrier
	s_setprio 1
	s_waitcnt lgkmcnt(0)
	v_mfma_f32_16x16x32_bf16 v[124:127], v[140:143], v[172:175], 0
	v_mfma_f32_16x16x32_bf16 v[128:131], v[148:151], v[172:175], 0
	v_mfma_f32_16x16x32_bf16 v[112:115], v[140:143], v[180:183], 0
	v_mfma_f32_16x16x32_bf16 v[108:111], v[148:151], v[180:183], 0
	v_mfma_f32_16x16x32_bf16 v[96:99], v[140:143], v[188:191], 0
	v_mfma_f32_16x16x32_bf16 v[92:95], v[148:151], v[188:191], 0
	v_mfma_f32_16x16x32_bf16 v[80:83], v[140:143], v[216:219], 0
	v_mfma_f32_16x16x32_bf16 v[76:79], v[148:151], v[216:219], 0
	v_mfma_f32_16x16x32_bf16 v[124:127], v[144:147], v[176:179], v[124:127]
	v_mfma_f32_16x16x32_bf16 v[128:131], v[152:155], v[176:179], v[128:131]
	v_mfma_f32_16x16x32_bf16 v[112:115], v[144:147], v[184:187], v[112:115]
	v_mfma_f32_16x16x32_bf16 v[108:111], v[152:155], v[184:187], v[108:111]
	v_mfma_f32_16x16x32_bf16 v[96:99], v[144:147], v[212:215], v[96:99]
	v_mfma_f32_16x16x32_bf16 v[92:95], v[152:155], v[212:215], v[92:95]
	v_mfma_f32_16x16x32_bf16 v[80:83], v[144:147], v[220:223], v[80:83]
	v_mfma_f32_16x16x32_bf16 v[76:79], v[152:155], v[220:223], v[76:79]
	s_setprio 0
	s_setprio 1
	v_mfma_f32_16x16x32_bf16 v[120:123], v[156:159], v[172:175], 0
	v_mfma_f32_16x16x32_bf16 v[116:119], v[164:167], v[172:175], 0
	v_mfma_f32_16x16x32_bf16 v[104:107], v[156:159], v[180:183], 0
	v_mfma_f32_16x16x32_bf16 v[100:103], v[164:167], v[180:183], 0
	v_mfma_f32_16x16x32_bf16 v[88:91], v[156:159], v[188:191], 0
	v_mfma_f32_16x16x32_bf16 v[84:87], v[164:167], v[188:191], 0
	v_mfma_f32_16x16x32_bf16 v[72:75], v[156:159], v[216:219], 0
	v_mfma_f32_16x16x32_bf16 v[68:71], v[164:167], v[216:219], 0
	v_mfma_f32_16x16x32_bf16 v[120:123], v[160:163], v[176:179], v[120:123]
	v_mfma_f32_16x16x32_bf16 v[116:119], v[168:171], v[176:179], v[116:119]
	v_mfma_f32_16x16x32_bf16 v[104:107], v[160:163], v[184:187], v[104:107]
	v_mfma_f32_16x16x32_bf16 v[100:103], v[168:171], v[184:187], v[100:103]
	v_mfma_f32_16x16x32_bf16 v[88:91], v[160:163], v[212:215], v[88:91]
	v_mfma_f32_16x16x32_bf16 v[84:87], v[168:171], v[212:215], v[84:87]
	v_mfma_f32_16x16x32_bf16 v[72:75], v[160:163], v[220:223], v[72:75]
	v_mfma_f32_16x16x32_bf16 v[68:71], v[168:171], v[220:223], v[68:71]
	s_setprio 0
	s_barrier
	s_add_i32 s9, s9, s14
	v_lshl_add_u64 v[208:209], v[208:209], 0, v[192:193]
	s_mov_b32 m0, s9
	ds_read_b128 v[172:175], v233 offset:16384
	ds_read_b128 v[176:179], v233 offset:17408
	ds_read_b128 v[180:183], v233 offset:18432
	ds_read_b128 v[184:187], v233 offset:19456
	ds_read_b128 v[188:191], v233 offset:20480
	ds_read_b128 v[212:215], v233 offset:21504
	ds_read_b128 v[216:219], v233 offset:22528
	ds_read_b128 v[220:223], v233 offset:23552
	global_load_lds_dwordx4 v[208:209], off
	v_lshl_add_u64 v[224:225], v[208:209], 0, s[84:85]
	s_add_i32 m0, s9, 0x2000
	s_add_i32 s9, s12, s14
	global_load_lds_dwordx4 v[224:225], off
	v_lshl_add_u64 v[224:225], v[208:209], 0, s[50:51]
	s_mov_b32 m0, s9
	v_lshl_add_u64 v[206:207], v[206:207], 0, v[194:195]
	global_load_lds_dwordx4 v[224:225], off
	v_lshl_add_u64 v[224:225], v[208:209], 0, s[94:95]
	s_add_i32 m0, s9, 0x2000
	s_nop 0
	global_load_lds_dwordx4 v[224:225], off
	s_mov_b32 m0, s16
	v_lshl_add_u64 v[224:225], v[206:207], 0, s[84:85]
	global_load_lds_dwordx4 v[206:207], off
	s_mov_b32 m0, s17
	s_nop 0
	global_load_lds_dwordx4 v[224:225], off
	s_waitcnt vmcnt(24)
	s_waitcnt lgkmcnt(0)
	s_barrier
	s_setprio 1
	s_waitcnt lgkmcnt(0)
	v_mfma_f32_16x16x32_bf16 v[64:67], v[140:143], v[172:175], 0
	v_mfma_f32_16x16x32_bf16 v[60:63], v[148:151], v[172:175], 0
	v_mfma_f32_16x16x32_bf16 v[48:51], v[140:143], v[180:183], 0
	v_mfma_f32_16x16x32_bf16 v[44:47], v[148:151], v[180:183], 0
	v_mfma_f32_16x16x32_bf16 v[32:35], v[140:143], v[188:191], 0
	v_mfma_f32_16x16x32_bf16 v[28:31], v[148:151], v[188:191], 0
	v_mfma_f32_16x16x32_bf16 v[16:19], v[140:143], v[216:219], 0
	v_mfma_f32_16x16x32_bf16 v[12:15], v[148:151], v[216:219], 0
	v_mfma_f32_16x16x32_bf16 v[64:67], v[144:147], v[176:179], v[64:67]
	v_mfma_f32_16x16x32_bf16 v[60:63], v[152:155], v[176:179], v[60:63]
	v_mfma_f32_16x16x32_bf16 v[48:51], v[144:147], v[184:187], v[48:51]
	v_mfma_f32_16x16x32_bf16 v[44:47], v[152:155], v[184:187], v[44:47]
	v_mfma_f32_16x16x32_bf16 v[32:35], v[144:147], v[212:215], v[32:35]
	v_mfma_f32_16x16x32_bf16 v[28:31], v[152:155], v[212:215], v[28:31]
	v_mfma_f32_16x16x32_bf16 v[16:19], v[144:147], v[220:223], v[16:19]
	v_mfma_f32_16x16x32_bf16 v[12:15], v[152:155], v[220:223], v[12:15]
	s_setprio 0
	s_setprio 1
	v_mfma_f32_16x16x32_bf16 v[56:59], v[156:159], v[172:175], 0
	v_mfma_f32_16x16x32_bf16 v[52:55], v[164:167], v[172:175], 0
	v_mfma_f32_16x16x32_bf16 v[40:43], v[156:159], v[180:183], 0
	v_mfma_f32_16x16x32_bf16 v[36:39], v[164:167], v[180:183], 0
	v_mfma_f32_16x16x32_bf16 v[24:27], v[156:159], v[188:191], 0
	v_mfma_f32_16x16x32_bf16 v[20:23], v[164:167], v[188:191], 0
	v_mfma_f32_16x16x32_bf16 v[8:11], v[156:159], v[216:219], 0
	v_mfma_f32_16x16x32_bf16 v[4:7], v[164:167], v[216:219], 0
	v_mfma_f32_16x16x32_bf16 v[56:59], v[160:163], v[176:179], v[56:59]
	v_mfma_f32_16x16x32_bf16 v[52:55], v[168:171], v[176:179], v[52:55]
	v_mfma_f32_16x16x32_bf16 v[40:43], v[160:163], v[184:187], v[40:43]
	v_mfma_f32_16x16x32_bf16 v[36:39], v[168:171], v[184:187], v[36:39]
	v_mfma_f32_16x16x32_bf16 v[24:27], v[160:163], v[212:215], v[24:27]
	v_mfma_f32_16x16x32_bf16 v[20:23], v[168:171], v[212:215], v[20:23]
	v_mfma_f32_16x16x32_bf16 v[8:11], v[160:163], v[220:223], v[8:11]
	v_mfma_f32_16x16x32_bf16 v[4:7], v[168:171], v[220:223], v[4:7]
	s_setprio 0
	s_barrier
	s_add_i32 s9, 0, 0x18000
	v_add_u32_e32 v136, s9, v231
	s_add_i32 s12, 0, 0x1c000
	ds_read_b128 v[140:143], v136
	ds_read_b128 v[144:147], v136 offset:1024
	ds_read_b128 v[148:151], v136 offset:2048
	ds_read_b128 v[152:155], v136 offset:3072
	v_add_u32_e32 v136, s12, v231
	ds_read_b128 v[156:159], v136
	ds_read_b128 v[160:163], v136 offset:1024
	ds_read_b128 v[164:167], v136 offset:2048
	ds_read_b128 v[168:171], v136 offset:3072
	s_mov_b32 m0, s20
	v_lshl_add_u64 v[224:225], v[206:207], 0, s[50:51]
	ds_read_b128 v[172:175], v233 offset:32768
	ds_read_b128 v[176:179], v233 offset:33792
	ds_read_b128 v[180:183], v233 offset:34816
	ds_read_b128 v[184:187], v233 offset:35840
	ds_read_b128 v[188:191], v233 offset:36864
	ds_read_b128 v[212:215], v233 offset:37888
	ds_read_b128 v[216:219], v233 offset:38912
	ds_read_b128 v[220:223], v233 offset:39936
	global_load_lds_dwordx4 v[224:225], off
	v_lshl_add_u64 v[224:225], v[206:207], 0, s[94:95]
	s_mov_b32 m0, s21
	s_nop 0
	global_load_lds_dwordx4 v[224:225], off
	s_waitcnt vmcnt(8)
	s_waitcnt lgkmcnt(0)
	s_barrier
	s_setprio 1
	s_waitcnt lgkmcnt(0)
	v_mfma_f32_16x16x32_bf16 v[124:127], v[140:143], v[172:175], v[124:127]
	v_mfma_f32_16x16x32_bf16 v[128:131], v[148:151], v[172:175], v[128:131]
	v_mfma_f32_16x16x32_bf16 v[112:115], v[140:143], v[180:183], v[112:115]
	v_mfma_f32_16x16x32_bf16 v[108:111], v[148:151], v[180:183], v[108:111]
	v_mfma_f32_16x16x32_bf16 v[96:99], v[140:143], v[188:191], v[96:99]
	v_mfma_f32_16x16x32_bf16 v[92:95], v[148:151], v[188:191], v[92:95]
	v_mfma_f32_16x16x32_bf16 v[80:83], v[140:143], v[216:219], v[80:83]
	v_mfma_f32_16x16x32_bf16 v[76:79], v[148:151], v[216:219], v[76:79]
	v_mfma_f32_16x16x32_bf16 v[124:127], v[144:147], v[176:179], v[124:127]
	v_mfma_f32_16x16x32_bf16 v[128:131], v[152:155], v[176:179], v[128:131]
	v_mfma_f32_16x16x32_bf16 v[112:115], v[144:147], v[184:187], v[112:115]
	v_mfma_f32_16x16x32_bf16 v[108:111], v[152:155], v[184:187], v[108:111]
	v_mfma_f32_16x16x32_bf16 v[96:99], v[144:147], v[212:215], v[96:99]
	v_mfma_f32_16x16x32_bf16 v[92:95], v[152:155], v[212:215], v[92:95]
	v_mfma_f32_16x16x32_bf16 v[80:83], v[144:147], v[220:223], v[80:83]
	v_mfma_f32_16x16x32_bf16 v[76:79], v[152:155], v[220:223], v[76:79]
	s_setprio 0
	s_setprio 1
	v_mfma_f32_16x16x32_bf16 v[120:123], v[156:159], v[172:175], v[120:123]
	v_mfma_f32_16x16x32_bf16 v[116:119], v[164:167], v[172:175], v[116:119]
	v_mfma_f32_16x16x32_bf16 v[104:107], v[156:159], v[180:183], v[104:107]
	v_mfma_f32_16x16x32_bf16 v[100:103], v[164:167], v[180:183], v[100:103]
	v_mfma_f32_16x16x32_bf16 v[88:91], v[156:159], v[188:191], v[88:91]
	v_mfma_f32_16x16x32_bf16 v[84:87], v[164:167], v[188:191], v[84:87]
	v_mfma_f32_16x16x32_bf16 v[72:75], v[156:159], v[216:219], v[72:75]
	v_mfma_f32_16x16x32_bf16 v[68:71], v[164:167], v[216:219], v[68:71]
	v_mfma_f32_16x16x32_bf16 v[120:123], v[160:163], v[176:179], v[120:123]
	v_mfma_f32_16x16x32_bf16 v[116:119], v[168:171], v[176:179], v[116:119]
	v_mfma_f32_16x16x32_bf16 v[104:107], v[160:163], v[184:187], v[104:107]
	v_mfma_f32_16x16x32_bf16 v[100:103], v[168:171], v[184:187], v[100:103]
	v_mfma_f32_16x16x32_bf16 v[88:91], v[160:163], v[212:215], v[88:91]
	v_mfma_f32_16x16x32_bf16 v[84:87], v[168:171], v[212:215], v[84:87]
	v_mfma_f32_16x16x32_bf16 v[72:75], v[160:163], v[220:223], v[72:75]
	v_mfma_f32_16x16x32_bf16 v[68:71], v[168:171], v[220:223], v[68:71]
	s_setprio 0
	s_barrier
	s_add_i32 s9, s9, s14
	v_lshl_add_u64 v[224:225], v[208:209], 0, s[62:63]
	s_mov_b32 m0, s9
	ds_read_b128 v[172:175], v233 offset:49152
	ds_read_b128 v[176:179], v233 offset:50176
	ds_read_b128 v[180:183], v233 offset:51200
	ds_read_b128 v[184:187], v233 offset:52224
	ds_read_b128 v[188:191], v233 offset:53248
	ds_read_b128 v[212:215], v233 offset:54272
	ds_read_b128 v[216:219], v233 offset:55296
	ds_read_b128 v[220:223], v233 offset:56320
	global_load_lds_dwordx4 v[224:225], off
	v_lshl_add_u64 v[224:225], v[208:209], 0, s[70:71]
	s_add_i32 m0, s9, 0x2000
	s_add_i32 s9, s12, s14
	global_load_lds_dwordx4 v[224:225], off
	v_lshl_add_u64 v[224:225], v[208:209], 0, s[96:97]
	s_mov_b32 m0, s9
	v_lshl_add_u64 v[208:209], v[208:209], 0, s[88:89]
	global_load_lds_dwordx4 v[224:225], off
	s_add_i32 m0, s9, 0x2000
	s_nop 0
	global_load_lds_dwordx4 v[208:209], off
	v_lshl_add_u64 v[208:209], v[206:207], 0, s[62:63]
	s_mov_b32 m0, s22
	v_lshl_add_u64 v[206:207], v[206:207], 0, s[70:71]
	global_load_lds_dwordx4 v[208:209], off
	s_mov_b32 m0, s23
	s_nop 0
	global_load_lds_dwordx4 v[206:207], off
	s_waitcnt vmcnt(8)
	s_waitcnt lgkmcnt(0)
	s_barrier
	s_setprio 1
	s_waitcnt lgkmcnt(0)
	v_mfma_f32_16x16x32_bf16 v[64:67], v[140:143], v[172:175], v[64:67]
	v_mfma_f32_16x16x32_bf16 v[60:63], v[148:151], v[172:175], v[60:63]
	v_mfma_f32_16x16x32_bf16 v[48:51], v[140:143], v[180:183], v[48:51]
	v_mfma_f32_16x16x32_bf16 v[44:47], v[148:151], v[180:183], v[44:47]
	v_mfma_f32_16x16x32_bf16 v[32:35], v[140:143], v[188:191], v[32:35]
	v_mfma_f32_16x16x32_bf16 v[28:31], v[148:151], v[188:191], v[28:31]
	v_mfma_f32_16x16x32_bf16 v[16:19], v[140:143], v[216:219], v[16:19]
	v_mfma_f32_16x16x32_bf16 v[12:15], v[148:151], v[216:219], v[12:15]
	v_mfma_f32_16x16x32_bf16 v[64:67], v[144:147], v[176:179], v[64:67]
	v_mfma_f32_16x16x32_bf16 v[60:63], v[152:155], v[176:179], v[60:63]
	v_mfma_f32_16x16x32_bf16 v[48:51], v[144:147], v[184:187], v[48:51]
	v_mfma_f32_16x16x32_bf16 v[44:47], v[152:155], v[184:187], v[44:47]
	v_mfma_f32_16x16x32_bf16 v[32:35], v[144:147], v[212:215], v[32:35]
	v_mfma_f32_16x16x32_bf16 v[28:31], v[152:155], v[212:215], v[28:31]
	v_mfma_f32_16x16x32_bf16 v[16:19], v[144:147], v[220:223], v[16:19]
	v_mfma_f32_16x16x32_bf16 v[12:15], v[152:155], v[220:223], v[12:15]
	s_setprio 0
	s_setprio 1
	v_mfma_f32_16x16x32_bf16 v[56:59], v[156:159], v[172:175], v[56:59]
	v_mfma_f32_16x16x32_bf16 v[52:55], v[164:167], v[172:175], v[52:55]
	v_mfma_f32_16x16x32_bf16 v[40:43], v[156:159], v[180:183], v[40:43]
	v_mfma_f32_16x16x32_bf16 v[36:39], v[164:167], v[180:183], v[36:39]
	v_mfma_f32_16x16x32_bf16 v[24:27], v[156:159], v[188:191], v[24:27]
	v_mfma_f32_16x16x32_bf16 v[20:23], v[164:167], v[188:191], v[20:23]
	v_mfma_f32_16x16x32_bf16 v[8:11], v[156:159], v[216:219], v[8:11]
	v_mfma_f32_16x16x32_bf16 v[4:7], v[164:167], v[216:219], v[4:7]
	v_mfma_f32_16x16x32_bf16 v[56:59], v[160:163], v[176:179], v[56:59]
	v_mfma_f32_16x16x32_bf16 v[52:55], v[168:171], v[176:179], v[52:55]
	v_mfma_f32_16x16x32_bf16 v[40:43], v[160:163], v[184:187], v[40:43]
	v_mfma_f32_16x16x32_bf16 v[36:39], v[168:171], v[184:187], v[36:39]
	v_mfma_f32_16x16x32_bf16 v[24:27], v[160:163], v[212:215], v[24:27]
	v_mfma_f32_16x16x32_bf16 v[20:23], v[168:171], v[212:215], v[20:23]
	v_mfma_f32_16x16x32_bf16 v[8:11], v[160:163], v[220:223], v[8:11]
	v_mfma_f32_16x16x32_bf16 v[4:7], v[168:171], v[220:223], v[4:7]
	s_setprio 0
	s_barrier
	s_add_i32 s7, s7, 2
	v_lshl_add_u64 v[138:139], v[138:139], 0, s[72:73]
	s_cmpk_gt_u32 s7, 0x7d
	v_lshl_add_u64 v[132:133], v[132:133], 0, s[72:73]
